# GEMM mainloops: extra s_setprio 0/1 flip after every 8 MFMAs (partner issue windows) on top of pipelined PV reads
# baseline (speedup 1.0000x reference)
; #define PG8_STAGE(bufoff, gbase, voff) do { _Pragma("unroll") for (int _i = 0; _i < 2; ++_i) \
;         __builtin_amdgcn_global_load_lds((const unsigned*)((const char*)(gbase) + (voff)[_i]), (LAS unsigned*)(lds + (bufoff) + ldsw + _i * 8192), 16, 0, 0); } while (0)
; #define PG8_LDA(dst, b, h) do { _Pragma("unroll") for (int m = 0; m < 4; ++m) _Pragma("unroll") for (int k = 0; k < 2; ++k) dst[m][k] = *(const LAS bf16x8*)(lds + PG8_SA(b, h) + aoff + m * 2048 + k * 1024); } while (0)
; #define PG8_LDB(dst, b, h) do { _Pragma("unroll") for (int n = 0; n < 2; ++n) _Pragma("unroll") for (int k = 0; k < 2; ++k) dst[n][k] = *(const LAS bf16x8*)(lds + PG8_SB(b, h) + boff + n * 2048 + k * 1024); } while (0)
; #define PG8_MMA(ai, bj, At, Bt) do { __builtin_amdgcn_s_setprio(1); _Pragma("unroll") for (int m = 0; m < 4; ++m) _Pragma("unroll") for (int n = 0; n < 2; ++n) _Pragma("unroll") for (int k = 0; k < 2; ++k) \
;         acc[ai][bj][m][n] = __builtin_amdgcn_mfma_f32_16x16x32_bf16(Bt[n][k], At[m][k], acc[ai][bj][m][n], 0, 0, 0); __builtin_amdgcn_s_setprio(0); } while (0)
; #define PG8_WAIT_V(n) asm volatile("s_waitcnt vmcnt(" #n ")" ::: "memory")
; #define PG8_WAIT_L(n) asm volatile("s_waitcnt lgkmcnt(" #n ")" ::: "memory")
; #define PG8_BAR __builtin_amdgcn_s_barrier()
; #define PG8_SCHED __builtin_amdgcn_sched_barrier(0)
; template <class Epi>
; __device__ __forceinline__ void gemm_phase(LAS unsigned char* lds, const Gemm g, const StaticOrder& S, const Epi& E) {
;     ...
;             const bool last = (t == nt - 2);
;             const char* a1 = cA + (size_t)(t + 1) * kstep;
;             const char* a2 = last ? nA : cA + (size_t)(t + 2) * kstep; const char* b2 = last ? nB : cB + (size_t)(t + 2) * kstep;
;             const char* a3 = a2 + kstep; const char* b3 = b2 + kstep;
;             PG8_LDB(B0, 0, 0); PG8_LDB(B1, 0, 1); PG8_SCHED; PG8_LDA(At, 0, 0); PG8_STAGE(PG8_SA(1, 1), a1 + hstepA, voffA);
;             PG8_WAIT_V(8); PG8_WAIT_L(0); PG8_BAR; PG8_MMA(0, 0, At, B0); PG8_MMA(0, 1, At, B1); PG8_BAR; PG8_SCHED;
;             PG8_LDA(At, 0, 1); PG8_STAGE(PG8_SB(0, 0), b2, voffB); PG8_STAGE(PG8_SB(0, 1), b2 + hstepB, voffB); PG8_STAGE(PG8_SA(0, 0), a2, voffA);
;             PG8_WAIT_V(8); PG8_WAIT_L(0); PG8_BAR; PG8_MMA(1, 0, At, B0); PG8_MMA(1, 1, At, B1); PG8_BAR; PG8_SCHED;
.LBB0_194:
	s_add_i32 s66, s28, 2
	s_add_u32 s29, s4, 0xfff80080
	s_addc_u32 s46, s5, -1
	s_add_i32 s93, 0, 0x10000
	s_cmp_eq_u32 s61, s28
	s_cselect_b32 s47, s9, s46
	s_cselect_b32 s46, s19, s29
	v_add_u32_e32 v152, s93, v179
	s_cselect_b32 s29, s21, s65
	s_cselect_b32 s28, s36, s37
	s_add_i32 s44, 0, 0x14000
	ds_read_b128 v[130:133], v152
	ds_read_b128 v[134:137], v152 offset:1024
	ds_read_b128 v[148:151], v152 offset:2048
	ds_read_b128 v[166:169], v152 offset:3072
	v_add_u32_e32 v152, s44, v179
	ds_read_b128 v[170:173], v152
	ds_read_b128 v[174:177], v152 offset:1024
	ds_read_b128 v[182:185], v152 offset:2048
	ds_read_b128 v[186:189], v152 offset:3072
	v_lshl_add_u64 v[152:153], s[4:5], 0, v[146:147]
	s_add_i32 m0, s52, 0xc000
	ds_read_b128 v[190:193], v180
	ds_read_b128 v[194:197], v180 offset:1024
	ds_read_b128 v[198:201], v180 offset:2048
	ds_read_b128 v[224:227], v180 offset:3072
	ds_read_b128 v[228:231], v180 offset:4096
	ds_read_b128 v[232:235], v180 offset:5120
	ds_read_b128 v[236:239], v180 offset:6144
	ds_read_b128 v[240:243], v180 offset:7168
	global_load_lds_dwordx4 v[152:153], off
	v_lshl_add_u64 v[152:153], s[4:5], 0, v[144:145]
	s_add_i32 m0, s52, 0xe000
	s_nop 0
	global_load_lds_dwordx4 v[152:153], off
	s_waitcnt vmcnt(8)
	s_waitcnt lgkmcnt(0)
	s_barrier
	s_setprio 1
	s_waitcnt lgkmcnt(0)
	v_mfma_f32_16x16x32_bf16 v[126:129], v[130:133], v[190:193], v[126:129]
	v_mfma_f32_16x16x32_bf16 v[122:125], v[148:151], v[190:193], v[122:125]
	v_mfma_f32_16x16x32_bf16 v[110:113], v[130:133], v[198:201], v[110:113]
	v_mfma_f32_16x16x32_bf16 v[106:109], v[148:151], v[198:201], v[106:109]
	v_mfma_f32_16x16x32_bf16 v[94:97], v[130:133], v[228:231], v[94:97]
	v_mfma_f32_16x16x32_bf16 v[90:93], v[148:151], v[228:231], v[90:93]
	v_mfma_f32_16x16x32_bf16 v[78:81], v[130:133], v[236:239], v[78:81]
	v_mfma_f32_16x16x32_bf16 v[74:77], v[148:151], v[236:239], v[74:77]
	s_setprio 0
	s_setprio 1
	v_mfma_f32_16x16x32_bf16 v[126:129], v[134:137], v[194:197], v[126:129]
	v_mfma_f32_16x16x32_bf16 v[122:125], v[166:169], v[194:197], v[122:125]
	v_mfma_f32_16x16x32_bf16 v[110:113], v[134:137], v[224:227], v[110:113]
	v_mfma_f32_16x16x32_bf16 v[106:109], v[166:169], v[224:227], v[106:109]
	v_mfma_f32_16x16x32_bf16 v[94:97], v[134:137], v[232:235], v[94:97]
	v_mfma_f32_16x16x32_bf16 v[90:93], v[166:169], v[232:235], v[90:93]
	v_mfma_f32_16x16x32_bf16 v[78:81], v[134:137], v[240:243], v[78:81]
	v_mfma_f32_16x16x32_bf16 v[74:77], v[166:169], v[240:243], v[74:77]
	s_setprio 0
	s_setprio 1
	v_mfma_f32_16x16x32_bf16 v[118:121], v[170:173], v[190:193], v[118:121]
	v_mfma_f32_16x16x32_bf16 v[114:117], v[182:185], v[190:193], v[114:117]
	v_mfma_f32_16x16x32_bf16 v[102:105], v[170:173], v[198:201], v[102:105]
	v_mfma_f32_16x16x32_bf16 v[98:101], v[182:185], v[198:201], v[98:101]
	v_mfma_f32_16x16x32_bf16 v[86:89], v[170:173], v[228:231], v[86:89]
	v_mfma_f32_16x16x32_bf16 v[82:85], v[182:185], v[228:231], v[82:85]
	v_mfma_f32_16x16x32_bf16 v[70:73], v[170:173], v[236:239], v[70:73]
	v_mfma_f32_16x16x32_bf16 v[66:69], v[182:185], v[236:239], v[66:69]
	s_setprio 0
	s_setprio 1
	v_mfma_f32_16x16x32_bf16 v[118:121], v[174:177], v[194:197], v[118:121]
	v_mfma_f32_16x16x32_bf16 v[114:117], v[186:189], v[194:197], v[114:117]
	v_mfma_f32_16x16x32_bf16 v[102:105], v[174:177], v[224:227], v[102:105]
	v_mfma_f32_16x16x32_bf16 v[98:101], v[186:189], v[224:227], v[98:101]
	v_mfma_f32_16x16x32_bf16 v[86:89], v[174:177], v[232:235], v[86:89]
	v_mfma_f32_16x16x32_bf16 v[82:85], v[186:189], v[232:235], v[82:85]
	v_mfma_f32_16x16x32_bf16 v[70:73], v[174:177], v[240:243], v[70:73]
	v_mfma_f32_16x16x32_bf16 v[66:69], v[186:189], v[240:243], v[66:69]
	s_setprio 0
	s_barrier
	s_add_i32 s45, s93, s51
	v_lshl_add_u64 v[152:153], s[28:29], 0, v[0:1]
	s_mov_b32 m0, s45
	ds_read_b128 v[190:193], v180 offset:16384
	ds_read_b128 v[194:197], v180 offset:17408
	ds_read_b128 v[198:201], v180 offset:18432
	ds_read_b128 v[224:227], v180 offset:19456
	ds_read_b128 v[228:231], v180 offset:20480
	ds_read_b128 v[232:235], v180 offset:21504
	ds_read_b128 v[236:239], v180 offset:22528
	ds_read_b128 v[240:243], v180 offset:23552
	global_load_lds_dwordx4 v[152:153], off
	s_add_i32 m0, s45, 0x2000
	s_add_u32 vcc_lo, s28, 0x80000
	v_lshl_add_u64 v[202:203], s[28:29], 0, v[142:143]
	s_addc_u32 vcc_hi, s29, 0
	s_add_i32 s44, s44, s51
	global_load_lds_dwordx4 v[202:203], off
	v_lshl_add_u64 v[244:245], vcc, 0, v[0:1]
	s_mov_b32 m0, s44
	v_lshl_add_u64 v[246:247], s[46:47], 0, v[140:141]
	global_load_lds_dwordx4 v[244:245], off
	v_lshl_add_u64 v[244:245], vcc, 0, v[142:143]
	s_add_i32 m0, s44, 0x2000
	s_nop 0
	global_load_lds_dwordx4 v[244:245], off
	v_lshl_add_u64 v[244:245], s[46:47], 0, v[138:139]
	s_mov_b32 m0, s52
	s_nop 0
	global_load_lds_dwordx4 v[244:245], off
	s_mov_b32 m0, s53
	s_nop 0
	global_load_lds_dwordx4 v[246:247], off
	s_waitcnt vmcnt(8)
	s_waitcnt lgkmcnt(0)
	s_barrier
; #define PG8_STAGE(bufoff, gbase, voff) do { _Pragma("unroll") for (int _i = 0; _i < 2; ++_i) \
;         __builtin_amdgcn_global_load_lds((const unsigned*)((const char*)(gbase) + (voff)[_i]), (LAS unsigned*)(lds + (bufoff) + ldsw + _i * 8192), 16, 0, 0); } while (0)
; #define PG8_LDA(dst, b, h) do { _Pragma("unroll") for (int m = 0; m < 4; ++m) _Pragma("unroll") for (int k = 0; k < 2; ++k) dst[m][k] = *(const LAS bf16x8*)(lds + PG8_SA(b, h) + aoff + m * 2048 + k * 1024); } while (0)
; #define PG8_LDB(dst, b, h) do { _Pragma("unroll") for (int n = 0; n < 2; ++n) _Pragma("unroll") for (int k = 0; k < 2; ++k) dst[n][k] = *(const LAS bf16x8*)(lds + PG8_SB(b, h) + boff + n * 2048 + k * 1024); } while (0)
; #define PG8_MMA(ai, bj, At, Bt) do { __builtin_amdgcn_s_setprio(1); _Pragma("unroll") for (int m = 0; m < 4; ++m) _Pragma("unroll") for (int n = 0; n < 2; ++n) _Pragma("unroll") for (int k = 0; k < 2; ++k) \
;         acc[ai][bj][m][n] = __builtin_amdgcn_mfma_f32_16x16x32_bf16(Bt[n][k], At[m][k], acc[ai][bj][m][n], 0, 0, 0); __builtin_amdgcn_s_setprio(0); } while (0)
; #define PG8_WAIT_V(n) asm volatile("s_waitcnt vmcnt(" #n ")" ::: "memory")
; #define PG8_WAIT_L(n) asm volatile("s_waitcnt lgkmcnt(" #n ")" ::: "memory")
; #define PG8_BAR __builtin_amdgcn_s_barrier()
; #define PG8_SCHED __builtin_amdgcn_sched_barrier(0)
; template <class Epi>
; __device__ __forceinline__ void gemm_phase(LAS unsigned char* lds, const Gemm g, const StaticOrder& S, const Epi& E) {
;     ...
;             PG8_WAIT_V(8); PG8_WAIT_L(0); PG8_BAR; PG8_MMA(1, 0, At, B0); PG8_MMA(1, 1, At, B1); PG8_BAR; PG8_SCHED;
;             PG8_LDB(B0, 1, 0); PG8_LDB(B1, 1, 1); PG8_SCHED; PG8_LDA(At, 1, 0); PG8_STAGE(PG8_SA(0, 1), a2 + hstepA, voffA);
;             PG8_WAIT_V(8); PG8_WAIT_L(0); PG8_BAR; PG8_MMA(0, 0, At, B0); PG8_MMA(0, 1, At, B1); PG8_BAR; PG8_SCHED;
	s_setprio 1
	s_waitcnt lgkmcnt(0)
	v_mfma_f32_16x16x32_bf16 v[62:65], v[130:133], v[190:193], v[62:65]
	v_mfma_f32_16x16x32_bf16 v[58:61], v[148:151], v[190:193], v[58:61]
	v_mfma_f32_16x16x32_bf16 v[46:49], v[130:133], v[198:201], v[46:49]
	v_mfma_f32_16x16x32_bf16 v[42:45], v[148:151], v[198:201], v[42:45]
	v_mfma_f32_16x16x32_bf16 v[30:33], v[130:133], v[228:231], v[30:33]
	v_mfma_f32_16x16x32_bf16 v[26:29], v[148:151], v[228:231], v[26:29]
	v_mfma_f32_16x16x32_bf16 v[14:17], v[130:133], v[236:239], v[14:17]
	v_mfma_f32_16x16x32_bf16 v[10:13], v[148:151], v[236:239], v[10:13]
	s_setprio 0
	s_setprio 1
	v_mfma_f32_16x16x32_bf16 v[62:65], v[134:137], v[194:197], v[62:65]
	v_mfma_f32_16x16x32_bf16 v[58:61], v[166:169], v[194:197], v[58:61]
	v_mfma_f32_16x16x32_bf16 v[46:49], v[134:137], v[224:227], v[46:49]
	v_mfma_f32_16x16x32_bf16 v[42:45], v[166:169], v[224:227], v[42:45]
	v_mfma_f32_16x16x32_bf16 v[30:33], v[134:137], v[232:235], v[30:33]
	v_mfma_f32_16x16x32_bf16 v[26:29], v[166:169], v[232:235], v[26:29]
	v_mfma_f32_16x16x32_bf16 v[14:17], v[134:137], v[240:243], v[14:17]
	v_mfma_f32_16x16x32_bf16 v[10:13], v[166:169], v[240:243], v[10:13]
	s_setprio 0
	s_setprio 1
	v_mfma_f32_16x16x32_bf16 v[54:57], v[170:173], v[190:193], v[54:57]
	v_mfma_f32_16x16x32_bf16 v[50:53], v[182:185], v[190:193], v[50:53]
	v_mfma_f32_16x16x32_bf16 v[38:41], v[170:173], v[198:201], v[38:41]
	v_mfma_f32_16x16x32_bf16 v[34:37], v[182:185], v[198:201], v[34:37]
	v_mfma_f32_16x16x32_bf16 v[22:25], v[170:173], v[228:231], v[22:25]
	v_mfma_f32_16x16x32_bf16 v[18:21], v[182:185], v[228:231], v[18:21]
	v_mfma_f32_16x16x32_bf16 v[6:9], v[170:173], v[236:239], v[6:9]
	v_mfma_f32_16x16x32_bf16 v[2:5], v[182:185], v[236:239], v[2:5]
	s_setprio 0
	s_setprio 1
	v_mfma_f32_16x16x32_bf16 v[54:57], v[174:177], v[194:197], v[54:57]
	v_mfma_f32_16x16x32_bf16 v[50:53], v[186:189], v[194:197], v[50:53]
	v_mfma_f32_16x16x32_bf16 v[38:41], v[174:177], v[224:227], v[38:41]
	v_mfma_f32_16x16x32_bf16 v[34:37], v[186:189], v[224:227], v[34:37]
	v_mfma_f32_16x16x32_bf16 v[22:25], v[174:177], v[232:235], v[22:25]
	v_mfma_f32_16x16x32_bf16 v[18:21], v[186:189], v[232:235], v[18:21]
	v_mfma_f32_16x16x32_bf16 v[6:9], v[174:177], v[240:243], v[6:9]
	v_mfma_f32_16x16x32_bf16 v[2:5], v[186:189], v[240:243], v[2:5]
	s_setprio 0
	s_barrier
	s_add_i32 s44, 0, 0x18000
	s_add_i32 s45, 0, 0x1c000
	v_add_u32_e32 v166, s44, v179
	v_add_u32_e32 v181, s45, v179
	ds_read_b128 v[130:133], v166
	ds_read_b128 v[134:137], v166 offset:1024
	ds_read_b128 v[148:151], v166 offset:2048
	ds_read_b128 v[166:169], v166 offset:3072
	ds_read_b128 v[170:173], v181
	ds_read_b128 v[174:177], v181 offset:1024
	ds_read_b128 v[182:185], v181 offset:2048
	ds_read_b128 v[186:189], v181 offset:3072
	s_add_u32 s46, s46, 0x80000
	s_addc_u32 s47, s47, 0
	s_mov_b32 m0, s54
	v_lshl_add_u64 v[248:249], s[46:47], 0, v[138:139]
	ds_read_b128 v[190:193], v180 offset:32768
	ds_read_b128 v[194:197], v180 offset:33792
	ds_read_b128 v[198:201], v180 offset:34816
	ds_read_b128 v[224:227], v180 offset:35840
	ds_read_b128 v[228:231], v180 offset:36864
	ds_read_b128 v[232:235], v180 offset:37888
	ds_read_b128 v[236:239], v180 offset:38912
	ds_read_b128 v[240:243], v180 offset:39936
	global_load_lds_dwordx4 v[248:249], off
	v_lshl_add_u64 v[248:249], s[46:47], 0, v[140:141]
	s_mov_b32 m0, s55
	s_nop 0
	global_load_lds_dwordx4 v[248:249], off
	s_waitcnt vmcnt(8)
	s_waitcnt lgkmcnt(0)
	s_barrier
	s_setprio 1
	s_waitcnt lgkmcnt(0)
	v_mfma_f32_16x16x32_bf16 v[126:129], v[130:133], v[190:193], v[126:129]
	v_mfma_f32_16x16x32_bf16 v[122:125], v[148:151], v[190:193], v[122:125]
	v_mfma_f32_16x16x32_bf16 v[110:113], v[130:133], v[198:201], v[110:113]
	v_mfma_f32_16x16x32_bf16 v[106:109], v[148:151], v[198:201], v[106:109]
	v_mfma_f32_16x16x32_bf16 v[94:97], v[130:133], v[228:231], v[94:97]
	v_mfma_f32_16x16x32_bf16 v[90:93], v[148:151], v[228:231], v[90:93]
	v_mfma_f32_16x16x32_bf16 v[78:81], v[130:133], v[236:239], v[78:81]
	v_mfma_f32_16x16x32_bf16 v[74:77], v[148:151], v[236:239], v[74:77]
	s_setprio 0
	s_setprio 1
	v_mfma_f32_16x16x32_bf16 v[126:129], v[134:137], v[194:197], v[126:129]
	v_mfma_f32_16x16x32_bf16 v[122:125], v[166:169], v[194:197], v[122:125]
	v_mfma_f32_16x16x32_bf16 v[110:113], v[134:137], v[224:227], v[110:113]
	v_mfma_f32_16x16x32_bf16 v[106:109], v[166:169], v[224:227], v[106:109]
	v_mfma_f32_16x16x32_bf16 v[94:97], v[134:137], v[232:235], v[94:97]
	v_mfma_f32_16x16x32_bf16 v[90:93], v[166:169], v[232:235], v[90:93]
	v_mfma_f32_16x16x32_bf16 v[78:81], v[134:137], v[240:243], v[78:81]
	v_mfma_f32_16x16x32_bf16 v[74:77], v[166:169], v[240:243], v[74:77]
	s_setprio 0
	s_setprio 1
	v_mfma_f32_16x16x32_bf16 v[118:121], v[170:173], v[190:193], v[118:121]
	v_mfma_f32_16x16x32_bf16 v[114:117], v[182:185], v[190:193], v[114:117]
	v_mfma_f32_16x16x32_bf16 v[102:105], v[170:173], v[198:201], v[102:105]
	v_mfma_f32_16x16x32_bf16 v[98:101], v[182:185], v[198:201], v[98:101]
	v_mfma_f32_16x16x32_bf16 v[86:89], v[170:173], v[228:231], v[86:89]
	v_mfma_f32_16x16x32_bf16 v[82:85], v[182:185], v[228:231], v[82:85]
	v_mfma_f32_16x16x32_bf16 v[70:73], v[170:173], v[236:239], v[70:73]
	v_mfma_f32_16x16x32_bf16 v[66:69], v[182:185], v[236:239], v[66:69]
	s_setprio 0
	s_setprio 1
	v_mfma_f32_16x16x32_bf16 v[118:121], v[174:177], v[194:197], v[118:121]
	v_mfma_f32_16x16x32_bf16 v[114:117], v[186:189], v[194:197], v[114:117]
	v_mfma_f32_16x16x32_bf16 v[102:105], v[174:177], v[224:227], v[102:105]
	v_mfma_f32_16x16x32_bf16 v[98:101], v[186:189], v[224:227], v[98:101]
	v_mfma_f32_16x16x32_bf16 v[86:89], v[174:177], v[232:235], v[86:89]
	v_mfma_f32_16x16x32_bf16 v[82:85], v[186:189], v[232:235], v[82:85]
	v_mfma_f32_16x16x32_bf16 v[70:73], v[174:177], v[240:243], v[70:73]
	v_mfma_f32_16x16x32_bf16 v[66:69], v[186:189], v[240:243], v[66:69]
	s_setprio 0
	s_barrier
; #define PG8_STAGE(bufoff, gbase, voff) do { _Pragma("unroll") for (int _i = 0; _i < 2; ++_i) \
;         __builtin_amdgcn_global_load_lds((const unsigned*)((const char*)(gbase) + (voff)[_i]), (LAS unsigned*)(lds + (bufoff) + ldsw + _i * 8192), 16, 0, 0); } while (0)
; #define PG8_LDA(dst, b, h) do { _Pragma("unroll") for (int m = 0; m < 4; ++m) _Pragma("unroll") for (int k = 0; k < 2; ++k) dst[m][k] = *(const LAS bf16x8*)(lds + PG8_SA(b, h) + aoff + m * 2048 + k * 1024); } while (0)
; #define PG8_MMA(ai, bj, At, Bt) do { __builtin_amdgcn_s_setprio(1); _Pragma("unroll") for (int m = 0; m < 4; ++m) _Pragma("unroll") for (int n = 0; n < 2; ++n) _Pragma("unroll") for (int k = 0; k < 2; ++k) \
;         acc[ai][bj][m][n] = __builtin_amdgcn_mfma_f32_16x16x32_bf16(Bt[n][k], At[m][k], acc[ai][bj][m][n], 0, 0, 0); __builtin_amdgcn_s_setprio(0); } while (0)
; #define PG8_WAIT_V(n) asm volatile("s_waitcnt vmcnt(" #n ")" ::: "memory")
; #define PG8_WAIT_L(n) asm volatile("s_waitcnt lgkmcnt(" #n ")" ::: "memory")
; #define PG8_BAR __builtin_amdgcn_s_barrier()
; #define PG8_SCHED __builtin_amdgcn_sched_barrier(0)
; template <class Epi>
; __device__ __forceinline__ void gemm_phase(LAS unsigned char* lds, const Gemm g, const StaticOrder& S, const Epi& E) {
;     ...
;             PG8_LDA(At, 1, 1); PG8_STAGE(PG8_SB(1, 0), b3, voffB); PG8_STAGE(PG8_SB(1, 1), b3 + hstepB, voffB); PG8_STAGE(PG8_SA(1, 0), a3, voffA);
;             PG8_WAIT_V(8); PG8_WAIT_L(0); PG8_BAR; PG8_MMA(1, 0, At, B0); PG8_MMA(1, 1, At, B1); PG8_BAR; PG8_SCHED;
;         }
	s_add_i32 s44, s44, s51
	v_lshl_add_u64 v[152:153], v[152:153], 0, s[74:75]
	s_mov_b32 m0, s44
	ds_read_b128 v[190:193], v180 offset:49152
	ds_read_b128 v[194:197], v180 offset:50176
	ds_read_b128 v[198:201], v180 offset:51200
	ds_read_b128 v[224:227], v180 offset:52224
	ds_read_b128 v[228:231], v180 offset:53248
	ds_read_b128 v[232:235], v180 offset:54272
	ds_read_b128 v[236:239], v180 offset:55296
	ds_read_b128 v[240:243], v180 offset:56320
	global_load_lds_dwordx4 v[152:153], off
	s_add_i32 m0, s44, 0x2000
	s_add_u32 s28, s28, 0x80080
	v_lshl_add_u64 v[152:153], v[202:203], 0, s[74:75]
	s_addc_u32 s29, s29, 0
	s_add_i32 s44, s45, s51
	global_load_lds_dwordx4 v[152:153], off
	v_lshl_add_u64 v[152:153], s[28:29], 0, v[0:1]
	s_mov_b32 m0, s44
	s_nop 0
	global_load_lds_dwordx4 v[152:153], off
	v_lshl_add_u64 v[152:153], s[28:29], 0, v[142:143]
	s_add_i32 m0, s44, 0x2000
	s_nop 0
	global_load_lds_dwordx4 v[152:153], off
	v_lshl_add_u64 v[152:153], v[244:245], 0, s[74:75]
	s_mov_b32 m0, s59
	s_nop 0
	global_load_lds_dwordx4 v[152:153], off
	v_lshl_add_u64 v[152:153], v[246:247], 0, s[74:75]
	s_mov_b32 m0, s60
	s_nop 0
	global_load_lds_dwordx4 v[152:153], off
	s_waitcnt vmcnt(8)
	s_waitcnt lgkmcnt(0)
	s_barrier
	s_setprio 1
	s_waitcnt lgkmcnt(0)
	v_mfma_f32_16x16x32_bf16 v[62:65], v[130:133], v[190:193], v[62:65]
	v_mfma_f32_16x16x32_bf16 v[58:61], v[148:151], v[190:193], v[58:61]
	v_mfma_f32_16x16x32_bf16 v[46:49], v[130:133], v[198:201], v[46:49]
	v_mfma_f32_16x16x32_bf16 v[42:45], v[148:151], v[198:201], v[42:45]
	v_mfma_f32_16x16x32_bf16 v[30:33], v[130:133], v[228:231], v[30:33]
	v_mfma_f32_16x16x32_bf16 v[26:29], v[148:151], v[228:231], v[26:29]
	v_mfma_f32_16x16x32_bf16 v[14:17], v[130:133], v[236:239], v[14:17]
	v_mfma_f32_16x16x32_bf16 v[10:13], v[148:151], v[236:239], v[10:13]
	s_setprio 0
	s_setprio 1
	v_mfma_f32_16x16x32_bf16 v[62:65], v[134:137], v[194:197], v[62:65]
	v_mfma_f32_16x16x32_bf16 v[58:61], v[166:169], v[194:197], v[58:61]
	v_mfma_f32_16x16x32_bf16 v[46:49], v[134:137], v[224:227], v[46:49]
	v_mfma_f32_16x16x32_bf16 v[42:45], v[166:169], v[224:227], v[42:45]
	v_mfma_f32_16x16x32_bf16 v[30:33], v[134:137], v[232:235], v[30:33]
	v_mfma_f32_16x16x32_bf16 v[26:29], v[166:169], v[232:235], v[26:29]
	v_mfma_f32_16x16x32_bf16 v[14:17], v[134:137], v[240:243], v[14:17]
	v_mfma_f32_16x16x32_bf16 v[10:13], v[166:169], v[240:243], v[10:13]
	s_setprio 0
	s_setprio 1
	v_mfma_f32_16x16x32_bf16 v[54:57], v[170:173], v[190:193], v[54:57]
	v_mfma_f32_16x16x32_bf16 v[50:53], v[182:185], v[190:193], v[50:53]
	v_mfma_f32_16x16x32_bf16 v[38:41], v[170:173], v[198:201], v[38:41]
	v_mfma_f32_16x16x32_bf16 v[34:37], v[182:185], v[198:201], v[34:37]
	v_mfma_f32_16x16x32_bf16 v[22:25], v[170:173], v[228:231], v[22:25]
	v_mfma_f32_16x16x32_bf16 v[18:21], v[182:185], v[228:231], v[18:21]
	v_mfma_f32_16x16x32_bf16 v[6:9], v[170:173], v[236:239], v[6:9]
	v_mfma_f32_16x16x32_bf16 v[2:5], v[182:185], v[236:239], v[2:5]
	s_setprio 0
	s_setprio 1
	v_mfma_f32_16x16x32_bf16 v[54:57], v[174:177], v[194:197], v[54:57]
	v_mfma_f32_16x16x32_bf16 v[50:53], v[186:189], v[194:197], v[50:53]
	v_mfma_f32_16x16x32_bf16 v[38:41], v[174:177], v[224:227], v[38:41]
	v_mfma_f32_16x16x32_bf16 v[34:37], v[186:189], v[224:227], v[34:37]
	v_mfma_f32_16x16x32_bf16 v[22:25], v[174:177], v[232:235], v[22:25]
	v_mfma_f32_16x16x32_bf16 v[18:21], v[186:189], v[232:235], v[18:21]
	v_mfma_f32_16x16x32_bf16 v[6:9], v[174:177], v[240:243], v[6:9]
	v_mfma_f32_16x16x32_bf16 v[2:5], v[186:189], v[240:243], v[2:5]
	s_setprio 0
	s_barrier
	s_add_u32 s37, s37, 0x100
	s_addc_u32 s65, s65, 0
	s_add_u32 s4, s4, 0x100
	s_addc_u32 s5, s5, 0
	s_cmp_ge_i32 s66, s56
	s_mov_b32 s28, s66
	s_cbranch_scc0 .LBB0_194
	s_movk_i32 s93, 0x1000
	v_readlane_b32 s44, v254, 56

; #define PG8_STAGE(bufoff, gbase, voff) do { _Pragma("unroll") for (int _i = 0; _i < 2; ++_i) \
;         __builtin_amdgcn_global_load_lds((const unsigned*)((const char*)(gbase) + (voff)[_i]), (LAS unsigned*)(lds + (bufoff) + ldsw + _i * 8192), 16, 0, 0); } while (0)
; #define PG8_LDA(dst, b, h) do { _Pragma("unroll") for (int m = 0; m < 4; ++m) _Pragma("unroll") for (int k = 0; k < 2; ++k) dst[m][k] = *(const LAS bf16x8*)(lds + PG8_SA(b, h) + aoff + m * 2048 + k * 1024); } while (0)
; #define PG8_LDB(dst, b, h) do { _Pragma("unroll") for (int n = 0; n < 2; ++n) _Pragma("unroll") for (int k = 0; k < 2; ++k) dst[n][k] = *(const LAS bf16x8*)(lds + PG8_SB(b, h) + boff + n * 2048 + k * 1024); } while (0)
; #define PG8_MMA(ai, bj, At, Bt) do { __builtin_amdgcn_s_setprio(1); _Pragma("unroll") for (int m = 0; m < 4; ++m) _Pragma("unroll") for (int n = 0; n < 2; ++n) _Pragma("unroll") for (int k = 0; k < 2; ++k) \
;         acc[ai][bj][m][n] = __builtin_amdgcn_mfma_f32_16x16x32_bf16(Bt[n][k], At[m][k], acc[ai][bj][m][n], 0, 0, 0); __builtin_amdgcn_s_setprio(0); } while (0)
; #define PG8_WAIT_V(n) asm volatile("s_waitcnt vmcnt(" #n ")" ::: "memory")
; #define PG8_WAIT_L(n) asm volatile("s_waitcnt lgkmcnt(" #n ")" ::: "memory")
; #define PG8_BAR __builtin_amdgcn_s_barrier()
; #define PG8_SCHED __builtin_amdgcn_sched_barrier(0)
; template <class Epi>
; __device__ __forceinline__ void gemm_phase(LAS unsigned char* lds, const Gemm g, const StaticOrder& S, const Epi& E) {
;     ...
;             const bool last = (t == nt - 2);
;             const char* a1 = cA + (size_t)(t + 1) * kstep;
;             const char* a2 = last ? nA : cA + (size_t)(t + 2) * kstep; const char* b2 = last ? nB : cB + (size_t)(t + 2) * kstep;
;             const char* a3 = a2 + kstep; const char* b3 = b2 + kstep;
;             PG8_LDB(B0, 0, 0); PG8_LDB(B1, 0, 1); PG8_SCHED; PG8_LDA(At, 0, 0); PG8_STAGE(PG8_SA(1, 1), a1 + hstepA, voffA);
;             PG8_WAIT_V(8); PG8_WAIT_L(0); PG8_BAR; PG8_MMA(0, 0, At, B0); PG8_MMA(0, 1, At, B1); PG8_BAR; PG8_SCHED;
;             PG8_LDA(At, 0, 1); PG8_STAGE(PG8_SB(0, 0), b2, voffB); PG8_STAGE(PG8_SB(0, 1), b2 + hstepB, voffB); PG8_STAGE(PG8_SA(0, 0), a2, voffA);
;             PG8_WAIT_V(8); PG8_WAIT_L(0); PG8_BAR; PG8_MMA(1, 0, At, B0); PG8_MMA(1, 1, At, B1); PG8_BAR; PG8_SCHED;
.LBB0_338:
	s_waitcnt lgkmcnt(0)
	s_add_i32 s36, s21, 2
	s_add_u32 s8, s4, 0x100
	s_addc_u32 s9, s5, 0
	s_add_i32 s37, 0, 0x10000
	s_cmp_eq_u32 s11, s21
	s_cselect_b32 s55, s51, s9
	s_cselect_b32 s54, s50, s8
	v_add_u32_e32 v140, s37, v149
	s_cselect_b32 s29, s53, s19
	s_cselect_b32 s28, s52, s18
	s_add_i32 s21, 0, 0x14000
	ds_read_b128 v[166:169], v140
	ds_read_b128 v[170:173], v140 offset:1024
	ds_read_b128 v[174:177], v140 offset:2048
	ds_read_b128 v[178:181], v140 offset:3072
	v_add_u32_e32 v140, s21, v149
	ds_read_b128 v[182:185], v140
	ds_read_b128 v[186:189], v140 offset:1024
	ds_read_b128 v[190:193], v140 offset:2048
	ds_read_b128 v[194:197], v140 offset:3072
	v_lshl_add_u64 v[142:143], s[4:5], 0, v[138:139]
	s_add_i32 m0, s60, 0xc000
	ds_read_b128 v[198:201], v151
	ds_read_b128 v[224:227], v151 offset:1024
	ds_read_b128 v[228:231], v151 offset:2048
	ds_read_b128 v[232:235], v151 offset:3072
	ds_read_b128 v[236:239], v151 offset:4096
	ds_read_b128 v[240:243], v151 offset:5120
	ds_read_b128 v[244:247], v151 offset:6144
	ds_read_b128 v[248:251], v151 offset:7168
	global_load_lds_dwordx4 v[142:143], off
	v_lshl_add_u64 v[142:143], s[4:5], 0, v[136:137]
	s_add_i32 m0, s60, 0xe000
	s_nop 0
	global_load_lds_dwordx4 v[142:143], off
	s_waitcnt vmcnt(8)
	s_waitcnt lgkmcnt(0)
	s_barrier
	s_setprio 1
	s_waitcnt lgkmcnt(0)
	v_mfma_f32_16x16x32_bf16 v[126:129], v[166:169], v[198:201], v[126:129]
	v_mfma_f32_16x16x32_bf16 v[122:125], v[174:177], v[198:201], v[122:125]
	v_mfma_f32_16x16x32_bf16 v[118:121], v[166:169], v[228:231], v[118:121]
	v_mfma_f32_16x16x32_bf16 v[114:117], v[174:177], v[228:231], v[114:117]
	v_mfma_f32_16x16x32_bf16 v[110:113], v[166:169], v[236:239], v[110:113]
	v_mfma_f32_16x16x32_bf16 v[106:109], v[174:177], v[236:239], v[106:109]
	v_mfma_f32_16x16x32_bf16 v[102:105], v[166:169], v[244:247], v[102:105]
	v_mfma_f32_16x16x32_bf16 v[98:101], v[174:177], v[244:247], v[98:101]
	s_setprio 0
	s_setprio 1
	v_mfma_f32_16x16x32_bf16 v[126:129], v[170:173], v[224:227], v[126:129]
	v_mfma_f32_16x16x32_bf16 v[122:125], v[178:181], v[224:227], v[122:125]
	v_mfma_f32_16x16x32_bf16 v[118:121], v[170:173], v[232:235], v[118:121]
	v_mfma_f32_16x16x32_bf16 v[114:117], v[178:181], v[232:235], v[114:117]
	v_mfma_f32_16x16x32_bf16 v[110:113], v[170:173], v[240:243], v[110:113]
	v_mfma_f32_16x16x32_bf16 v[106:109], v[178:181], v[240:243], v[106:109]
	v_mfma_f32_16x16x32_bf16 v[102:105], v[170:173], v[248:251], v[102:105]
	v_mfma_f32_16x16x32_bf16 v[98:101], v[178:181], v[248:251], v[98:101]
	s_setprio 0
	s_setprio 1
	v_mfma_f32_16x16x32_bf16 v[62:65], v[182:185], v[198:201], v[62:65]
	v_mfma_f32_16x16x32_bf16 v[58:61], v[190:193], v[198:201], v[58:61]
	v_mfma_f32_16x16x32_bf16 v[54:57], v[182:185], v[228:231], v[54:57]
	v_mfma_f32_16x16x32_bf16 v[50:53], v[190:193], v[228:231], v[50:53]
	v_mfma_f32_16x16x32_bf16 v[46:49], v[182:185], v[236:239], v[46:49]
	v_mfma_f32_16x16x32_bf16 v[42:45], v[190:193], v[236:239], v[42:45]
	v_mfma_f32_16x16x32_bf16 v[38:41], v[182:185], v[244:247], v[38:41]
	v_mfma_f32_16x16x32_bf16 v[34:37], v[190:193], v[244:247], v[34:37]
	s_setprio 0
	s_setprio 1
	v_mfma_f32_16x16x32_bf16 v[62:65], v[186:189], v[224:227], v[62:65]
	v_mfma_f32_16x16x32_bf16 v[58:61], v[194:197], v[224:227], v[58:61]
	v_mfma_f32_16x16x32_bf16 v[54:57], v[186:189], v[232:235], v[54:57]
	v_mfma_f32_16x16x32_bf16 v[50:53], v[194:197], v[232:235], v[50:53]
	v_mfma_f32_16x16x32_bf16 v[46:49], v[186:189], v[240:243], v[46:49]
	v_mfma_f32_16x16x32_bf16 v[42:45], v[194:197], v[240:243], v[42:45]
	v_mfma_f32_16x16x32_bf16 v[38:41], v[186:189], v[248:251], v[38:41]
	v_mfma_f32_16x16x32_bf16 v[34:37], v[194:197], v[248:251], v[34:37]
	s_setprio 0
	s_barrier
	s_add_i32 s4, s37, s59
	v_lshl_add_u64 v[142:143], s[28:29], 0, v[0:1]
	s_mov_b32 m0, s4
	ds_read_b128 v[198:201], v151 offset:16384
	ds_read_b128 v[224:227], v151 offset:17408
	ds_read_b128 v[228:231], v151 offset:18432
	ds_read_b128 v[232:235], v151 offset:19456
	ds_read_b128 v[236:239], v151 offset:20480
	ds_read_b128 v[240:243], v151 offset:21504
	ds_read_b128 v[244:247], v151 offset:22528
	ds_read_b128 v[248:251], v151 offset:23552
	global_load_lds_dwordx4 v[142:143], off
	s_add_i32 m0, s4, 0x2000
	s_add_u32 s4, s28, 0x18000
	v_lshl_add_u64 v[146:147], s[28:29], 0, v[134:135]
	s_addc_u32 s5, s29, 0
	s_add_i32 s21, s21, s59
	global_load_lds_dwordx4 v[146:147], off
	v_lshl_add_u64 v[152:153], s[4:5], 0, v[0:1]
	s_mov_b32 m0, s21
	v_lshl_add_u64 v[202:203], s[54:55], 0, v[132:133]
	global_load_lds_dwordx4 v[152:153], off
	v_lshl_add_u64 v[152:153], s[4:5], 0, v[134:135]
	s_add_i32 m0, s21, 0x2000
	s_nop 0
	global_load_lds_dwordx4 v[152:153], off
	v_lshl_add_u64 v[152:153], s[54:55], 0, v[130:131]
	s_mov_b32 m0, s60
	s_nop 0
	global_load_lds_dwordx4 v[152:153], off
	s_mov_b32 m0, s61
	s_nop 0
	global_load_lds_dwordx4 v[202:203], off
	s_waitcnt vmcnt(8)
	s_waitcnt lgkmcnt(0)
	s_barrier
; #define PG8_STAGE(bufoff, gbase, voff) do { _Pragma("unroll") for (int _i = 0; _i < 2; ++_i) \
;         __builtin_amdgcn_global_load_lds((const unsigned*)((const char*)(gbase) + (voff)[_i]), (LAS unsigned*)(lds + (bufoff) + ldsw + _i * 8192), 16, 0, 0); } while (0)
; #define PG8_LDA(dst, b, h) do { _Pragma("unroll") for (int m = 0; m < 4; ++m) _Pragma("unroll") for (int k = 0; k < 2; ++k) dst[m][k] = *(const LAS bf16x8*)(lds + PG8_SA(b, h) + aoff + m * 2048 + k * 1024); } while (0)
; #define PG8_LDB(dst, b, h) do { _Pragma("unroll") for (int n = 0; n < 2; ++n) _Pragma("unroll") for (int k = 0; k < 2; ++k) dst[n][k] = *(const LAS bf16x8*)(lds + PG8_SB(b, h) + boff + n * 2048 + k * 1024); } while (0)
; #define PG8_MMA(ai, bj, At, Bt) do { __builtin_amdgcn_s_setprio(1); _Pragma("unroll") for (int m = 0; m < 4; ++m) _Pragma("unroll") for (int n = 0; n < 2; ++n) _Pragma("unroll") for (int k = 0; k < 2; ++k) \
;         acc[ai][bj][m][n] = __builtin_amdgcn_mfma_f32_16x16x32_bf16(Bt[n][k], At[m][k], acc[ai][bj][m][n], 0, 0, 0); __builtin_amdgcn_s_setprio(0); } while (0)
; #define PG8_WAIT_V(n) asm volatile("s_waitcnt vmcnt(" #n ")" ::: "memory")
; #define PG8_WAIT_L(n) asm volatile("s_waitcnt lgkmcnt(" #n ")" ::: "memory")
; #define PG8_BAR __builtin_amdgcn_s_barrier()
; #define PG8_SCHED __builtin_amdgcn_sched_barrier(0)
; template <class Epi>
; __device__ __forceinline__ void gemm_phase(LAS unsigned char* lds, const Gemm g, const StaticOrder& S, const Epi& E) {
;     ...
;             PG8_WAIT_V(8); PG8_WAIT_L(0); PG8_BAR; PG8_MMA(1, 0, At, B0); PG8_MMA(1, 1, At, B1); PG8_BAR; PG8_SCHED;
;             PG8_LDB(B0, 1, 0); PG8_LDB(B1, 1, 1); PG8_SCHED; PG8_LDA(At, 1, 0); PG8_STAGE(PG8_SA(0, 1), a2 + hstepA, voffA);
;             PG8_WAIT_V(8); PG8_WAIT_L(0); PG8_BAR; PG8_MMA(0, 0, At, B0); PG8_MMA(0, 1, At, B1); PG8_BAR; PG8_SCHED;
	s_setprio 1
	s_waitcnt lgkmcnt(0)
	v_mfma_f32_16x16x32_bf16 v[94:97], v[166:169], v[198:201], v[94:97]
	v_mfma_f32_16x16x32_bf16 v[90:93], v[174:177], v[198:201], v[90:93]
	v_mfma_f32_16x16x32_bf16 v[86:89], v[166:169], v[228:231], v[86:89]
	v_mfma_f32_16x16x32_bf16 v[82:85], v[174:177], v[228:231], v[82:85]
	v_mfma_f32_16x16x32_bf16 v[78:81], v[166:169], v[236:239], v[78:81]
	v_mfma_f32_16x16x32_bf16 v[74:77], v[174:177], v[236:239], v[74:77]
	v_mfma_f32_16x16x32_bf16 v[70:73], v[166:169], v[244:247], v[70:73]
	v_mfma_f32_16x16x32_bf16 v[66:69], v[174:177], v[244:247], v[66:69]
	s_setprio 0
	s_setprio 1
	v_mfma_f32_16x16x32_bf16 v[94:97], v[170:173], v[224:227], v[94:97]
	v_mfma_f32_16x16x32_bf16 v[90:93], v[178:181], v[224:227], v[90:93]
	v_mfma_f32_16x16x32_bf16 v[86:89], v[170:173], v[232:235], v[86:89]
	v_mfma_f32_16x16x32_bf16 v[82:85], v[178:181], v[232:235], v[82:85]
	v_mfma_f32_16x16x32_bf16 v[78:81], v[170:173], v[240:243], v[78:81]
	v_mfma_f32_16x16x32_bf16 v[74:77], v[178:181], v[240:243], v[74:77]
	v_mfma_f32_16x16x32_bf16 v[70:73], v[170:173], v[248:251], v[70:73]
	v_mfma_f32_16x16x32_bf16 v[66:69], v[178:181], v[248:251], v[66:69]
	s_setprio 0
	s_setprio 1
	v_mfma_f32_16x16x32_bf16 v[30:33], v[182:185], v[198:201], v[30:33]
	v_mfma_f32_16x16x32_bf16 v[26:29], v[190:193], v[198:201], v[26:29]
	v_mfma_f32_16x16x32_bf16 v[22:25], v[182:185], v[228:231], v[22:25]
	v_mfma_f32_16x16x32_bf16 v[18:21], v[190:193], v[228:231], v[18:21]
	v_mfma_f32_16x16x32_bf16 v[14:17], v[182:185], v[236:239], v[14:17]
	v_mfma_f32_16x16x32_bf16 v[10:13], v[190:193], v[236:239], v[10:13]
	v_mfma_f32_16x16x32_bf16 v[6:9], v[182:185], v[244:247], v[6:9]
	v_mfma_f32_16x16x32_bf16 v[2:5], v[190:193], v[244:247], v[2:5]
	s_setprio 0
	s_setprio 1
	v_mfma_f32_16x16x32_bf16 v[30:33], v[186:189], v[224:227], v[30:33]
	v_mfma_f32_16x16x32_bf16 v[26:29], v[194:197], v[224:227], v[26:29]
	v_mfma_f32_16x16x32_bf16 v[22:25], v[186:189], v[232:235], v[22:25]
	v_mfma_f32_16x16x32_bf16 v[18:21], v[194:197], v[232:235], v[18:21]
	v_mfma_f32_16x16x32_bf16 v[14:17], v[186:189], v[240:243], v[14:17]
	v_mfma_f32_16x16x32_bf16 v[10:13], v[194:197], v[240:243], v[10:13]
	v_mfma_f32_16x16x32_bf16 v[6:9], v[186:189], v[248:251], v[6:9]
	v_mfma_f32_16x16x32_bf16 v[2:5], v[194:197], v[248:251], v[2:5]
	s_setprio 0
	s_barrier
	s_add_i32 s21, 0, 0x18000
	v_add_u32_e32 v140, s21, v149
	s_add_i32 s37, 0, 0x1c000
	ds_read_b128 v[166:169], v140
	ds_read_b128 v[170:173], v140 offset:1024
	ds_read_b128 v[174:177], v140 offset:2048
	ds_read_b128 v[178:181], v140 offset:3072
	v_add_u32_e32 v140, s37, v149
	ds_read_b128 v[182:185], v140
	ds_read_b128 v[186:189], v140 offset:1024
	ds_read_b128 v[190:193], v140 offset:2048
	ds_read_b128 v[194:197], v140 offset:3072
	s_add_u32 s4, s54, 0xc0000
	s_addc_u32 s5, s55, 0
	s_mov_b32 m0, s62
	v_lshl_add_u64 v[252:253], s[4:5], 0, v[130:131]
	ds_read_b128 v[198:201], v151 offset:32768
	ds_read_b128 v[224:227], v151 offset:33792
	ds_read_b128 v[228:231], v151 offset:34816
	ds_read_b128 v[232:235], v151 offset:35840
	ds_read_b128 v[236:239], v151 offset:36864
	ds_read_b128 v[240:243], v151 offset:37888
	ds_read_b128 v[244:247], v151 offset:38912
	ds_read_b128 v[248:251], v151 offset:39936
	global_load_lds_dwordx4 v[252:253], off
	v_lshl_add_u64 v[252:253], s[4:5], 0, v[132:133]
	s_mov_b32 m0, s63
	s_nop 0
	global_load_lds_dwordx4 v[252:253], off
	s_waitcnt vmcnt(8)
	s_waitcnt lgkmcnt(0)
	s_barrier
	s_setprio 1
	s_waitcnt lgkmcnt(0)
	v_mfma_f32_16x16x32_bf16 v[126:129], v[166:169], v[198:201], v[126:129]
	v_mfma_f32_16x16x32_bf16 v[122:125], v[174:177], v[198:201], v[122:125]
	v_mfma_f32_16x16x32_bf16 v[118:121], v[166:169], v[228:231], v[118:121]
	v_mfma_f32_16x16x32_bf16 v[114:117], v[174:177], v[228:231], v[114:117]
	v_mfma_f32_16x16x32_bf16 v[110:113], v[166:169], v[236:239], v[110:113]
	v_mfma_f32_16x16x32_bf16 v[106:109], v[174:177], v[236:239], v[106:109]
	v_mfma_f32_16x16x32_bf16 v[102:105], v[166:169], v[244:247], v[102:105]
	v_mfma_f32_16x16x32_bf16 v[98:101], v[174:177], v[244:247], v[98:101]
	s_setprio 0
	s_setprio 1
	v_mfma_f32_16x16x32_bf16 v[126:129], v[170:173], v[224:227], v[126:129]
	v_mfma_f32_16x16x32_bf16 v[122:125], v[178:181], v[224:227], v[122:125]
	v_mfma_f32_16x16x32_bf16 v[118:121], v[170:173], v[232:235], v[118:121]
	v_mfma_f32_16x16x32_bf16 v[114:117], v[178:181], v[232:235], v[114:117]
	v_mfma_f32_16x16x32_bf16 v[110:113], v[170:173], v[240:243], v[110:113]
	v_mfma_f32_16x16x32_bf16 v[106:109], v[178:181], v[240:243], v[106:109]
	v_mfma_f32_16x16x32_bf16 v[102:105], v[170:173], v[248:251], v[102:105]
	v_mfma_f32_16x16x32_bf16 v[98:101], v[178:181], v[248:251], v[98:101]
	s_setprio 0
	s_setprio 1
	v_mfma_f32_16x16x32_bf16 v[62:65], v[182:185], v[198:201], v[62:65]
	v_mfma_f32_16x16x32_bf16 v[58:61], v[190:193], v[198:201], v[58:61]
	v_mfma_f32_16x16x32_bf16 v[54:57], v[182:185], v[228:231], v[54:57]
	v_mfma_f32_16x16x32_bf16 v[50:53], v[190:193], v[228:231], v[50:53]
	v_mfma_f32_16x16x32_bf16 v[46:49], v[182:185], v[236:239], v[46:49]
	v_mfma_f32_16x16x32_bf16 v[42:45], v[190:193], v[236:239], v[42:45]
	v_mfma_f32_16x16x32_bf16 v[38:41], v[182:185], v[244:247], v[38:41]
	v_mfma_f32_16x16x32_bf16 v[34:37], v[190:193], v[244:247], v[34:37]
	s_setprio 0
	s_setprio 1
	v_mfma_f32_16x16x32_bf16 v[62:65], v[186:189], v[224:227], v[62:65]
	v_mfma_f32_16x16x32_bf16 v[58:61], v[194:197], v[224:227], v[58:61]
	v_mfma_f32_16x16x32_bf16 v[54:57], v[186:189], v[232:235], v[54:57]
	v_mfma_f32_16x16x32_bf16 v[50:53], v[194:197], v[232:235], v[50:53]
	v_mfma_f32_16x16x32_bf16 v[46:49], v[186:189], v[240:243], v[46:49]
	v_mfma_f32_16x16x32_bf16 v[42:45], v[194:197], v[240:243], v[42:45]
	v_mfma_f32_16x16x32_bf16 v[38:41], v[186:189], v[248:251], v[38:41]
	v_mfma_f32_16x16x32_bf16 v[34:37], v[194:197], v[248:251], v[34:37]
	s_setprio 0
	s_barrier
; #define PG8_STAGE(bufoff, gbase, voff) do { _Pragma("unroll") for (int _i = 0; _i < 2; ++_i) \
;         __builtin_amdgcn_global_load_lds((const unsigned*)((const char*)(gbase) + (voff)[_i]), (LAS unsigned*)(lds + (bufoff) + ldsw + _i * 8192), 16, 0, 0); } while (0)
; #define PG8_LDA(dst, b, h) do { _Pragma("unroll") for (int m = 0; m < 4; ++m) _Pragma("unroll") for (int k = 0; k < 2; ++k) dst[m][k] = *(const LAS bf16x8*)(lds + PG8_SA(b, h) + aoff + m * 2048 + k * 1024); } while (0)
; #define PG8_MMA(ai, bj, At, Bt) do { __builtin_amdgcn_s_setprio(1); _Pragma("unroll") for (int m = 0; m < 4; ++m) _Pragma("unroll") for (int n = 0; n < 2; ++n) _Pragma("unroll") for (int k = 0; k < 2; ++k) \
;         acc[ai][bj][m][n] = __builtin_amdgcn_mfma_f32_16x16x32_bf16(Bt[n][k], At[m][k], acc[ai][bj][m][n], 0, 0, 0); __builtin_amdgcn_s_setprio(0); } while (0)
; #define PG8_WAIT_V(n) asm volatile("s_waitcnt vmcnt(" #n ")" ::: "memory")
; #define PG8_WAIT_L(n) asm volatile("s_waitcnt lgkmcnt(" #n ")" ::: "memory")
; #define PG8_BAR __builtin_amdgcn_s_barrier()
; #define PG8_SCHED __builtin_amdgcn_sched_barrier(0)
; template <class Epi>
; __device__ __forceinline__ void gemm_phase(LAS unsigned char* lds, const Gemm g, const StaticOrder& S, const Epi& E) {
;     ...
;             PG8_LDA(At, 1, 1); PG8_STAGE(PG8_SB(1, 0), b3, voffB); PG8_STAGE(PG8_SB(1, 1), b3 + hstepB, voffB); PG8_STAGE(PG8_SA(1, 0), a3, voffA);
;             PG8_WAIT_V(8); PG8_WAIT_L(0); PG8_BAR; PG8_MMA(1, 0, At, B0); PG8_MMA(1, 1, At, B1); PG8_BAR; PG8_SCHED;
;         }
	s_add_i32 s4, s21, s59
	v_lshl_add_u64 v[142:143], v[142:143], 0, s[74:75]
	s_mov_b32 m0, s4
	ds_read_b128 v[198:201], v151 offset:49152
	ds_read_b128 v[224:227], v151 offset:50176
	ds_read_b128 v[228:231], v151 offset:51200
	ds_read_b128 v[232:235], v151 offset:52224
	ds_read_b128 v[236:239], v151 offset:53248
	ds_read_b128 v[240:243], v151 offset:54272
	ds_read_b128 v[244:247], v151 offset:55296
	ds_read_b128 v[248:251], v151 offset:56320
	global_load_lds_dwordx4 v[142:143], off
	s_add_i32 m0, s4, 0x2000
	s_add_u32 s4, s28, 0x18080
	v_lshl_add_u64 v[142:143], v[146:147], 0, s[74:75]
	s_addc_u32 s5, s29, 0
	s_add_i32 s21, s37, s59
	global_load_lds_dwordx4 v[142:143], off
	v_lshl_add_u64 v[142:143], s[4:5], 0, v[0:1]
	s_mov_b32 m0, s21
	s_nop 0
	global_load_lds_dwordx4 v[142:143], off
	v_lshl_add_u64 v[142:143], s[4:5], 0, v[134:135]
	s_add_i32 m0, s21, 0x2000
	s_nop 0
	global_load_lds_dwordx4 v[142:143], off
	v_lshl_add_u64 v[142:143], v[152:153], 0, s[74:75]
	s_mov_b32 m0, s93
	s_nop 0
	global_load_lds_dwordx4 v[142:143], off
	v_lshl_add_u64 v[142:143], v[202:203], 0, s[74:75]
	s_mov_b32 m0, s10
	s_nop 0
	global_load_lds_dwordx4 v[142:143], off
	s_waitcnt vmcnt(8)
	s_waitcnt lgkmcnt(0)
	s_barrier
	s_setprio 1
	s_waitcnt lgkmcnt(0)
	v_mfma_f32_16x16x32_bf16 v[94:97], v[166:169], v[198:201], v[94:97]
	v_mfma_f32_16x16x32_bf16 v[90:93], v[174:177], v[198:201], v[90:93]
	v_mfma_f32_16x16x32_bf16 v[86:89], v[166:169], v[228:231], v[86:89]
	v_mfma_f32_16x16x32_bf16 v[82:85], v[174:177], v[228:231], v[82:85]
	v_mfma_f32_16x16x32_bf16 v[78:81], v[166:169], v[236:239], v[78:81]
	v_mfma_f32_16x16x32_bf16 v[74:77], v[174:177], v[236:239], v[74:77]
	v_mfma_f32_16x16x32_bf16 v[70:73], v[166:169], v[244:247], v[70:73]
	v_mfma_f32_16x16x32_bf16 v[66:69], v[174:177], v[244:247], v[66:69]
	s_setprio 0
	s_setprio 1
	v_mfma_f32_16x16x32_bf16 v[94:97], v[170:173], v[224:227], v[94:97]
	v_mfma_f32_16x16x32_bf16 v[90:93], v[178:181], v[224:227], v[90:93]
	v_mfma_f32_16x16x32_bf16 v[86:89], v[170:173], v[232:235], v[86:89]
	v_mfma_f32_16x16x32_bf16 v[82:85], v[178:181], v[232:235], v[82:85]
	v_mfma_f32_16x16x32_bf16 v[78:81], v[170:173], v[240:243], v[78:81]
	v_mfma_f32_16x16x32_bf16 v[74:77], v[178:181], v[240:243], v[74:77]
	v_mfma_f32_16x16x32_bf16 v[70:73], v[170:173], v[248:251], v[70:73]
	v_mfma_f32_16x16x32_bf16 v[66:69], v[178:181], v[248:251], v[66:69]
	s_setprio 0
	s_setprio 1
	v_mfma_f32_16x16x32_bf16 v[30:33], v[182:185], v[198:201], v[30:33]
	v_mfma_f32_16x16x32_bf16 v[26:29], v[190:193], v[198:201], v[26:29]
	v_mfma_f32_16x16x32_bf16 v[22:25], v[182:185], v[228:231], v[22:25]
	v_mfma_f32_16x16x32_bf16 v[18:21], v[190:193], v[228:231], v[18:21]
	v_mfma_f32_16x16x32_bf16 v[14:17], v[182:185], v[236:239], v[14:17]
	v_mfma_f32_16x16x32_bf16 v[10:13], v[190:193], v[236:239], v[10:13]
	v_mfma_f32_16x16x32_bf16 v[6:9], v[182:185], v[244:247], v[6:9]
	v_mfma_f32_16x16x32_bf16 v[2:5], v[190:193], v[244:247], v[2:5]
	s_setprio 0
	s_setprio 1
	v_mfma_f32_16x16x32_bf16 v[30:33], v[186:189], v[224:227], v[30:33]
	v_mfma_f32_16x16x32_bf16 v[26:29], v[194:197], v[224:227], v[26:29]
	v_mfma_f32_16x16x32_bf16 v[22:25], v[186:189], v[232:235], v[22:25]
	v_mfma_f32_16x16x32_bf16 v[18:21], v[194:197], v[232:235], v[18:21]
	v_mfma_f32_16x16x32_bf16 v[14:17], v[186:189], v[240:243], v[14:17]
	v_mfma_f32_16x16x32_bf16 v[10:13], v[194:197], v[240:243], v[10:13]
	v_mfma_f32_16x16x32_bf16 v[6:9], v[186:189], v[248:251], v[6:9]
	v_mfma_f32_16x16x32_bf16 v[2:5], v[194:197], v[248:251], v[2:5]
	s_setprio 0
	s_barrier
	s_add_u32 s18, s18, 0x100
	s_addc_u32 s19, s19, 0
	s_cmp_ge_i32 s36, s65
	s_mov_b64 s[4:5], s[8:9]
	s_mov_b32 s21, s36
	s_cbranch_scc0 .LBB0_338
	s_load_dwordx2 s[36:37], s[96:97], 0x8

; #define PG8_STAGE(bufoff, gbase, voff) do { _Pragma("unroll") for (int _i = 0; _i < 2; ++_i) \
;         __builtin_amdgcn_global_load_lds((const unsigned*)((const char*)(gbase) + (voff)[_i]), (LAS unsigned*)(lds + (bufoff) + ldsw + _i * 8192), 16, 0, 0); } while (0)
; #define PG8_LDA(dst, b, h) do { _Pragma("unroll") for (int m = 0; m < 4; ++m) _Pragma("unroll") for (int k = 0; k < 2; ++k) dst[m][k] = *(const LAS bf16x8*)(lds + PG8_SA(b, h) + aoff + m * 2048 + k * 1024); } while (0)
; #define PG8_LDB(dst, b, h) do { _Pragma("unroll") for (int n = 0; n < 2; ++n) _Pragma("unroll") for (int k = 0; k < 2; ++k) dst[n][k] = *(const LAS bf16x8*)(lds + PG8_SB(b, h) + boff + n * 2048 + k * 1024); } while (0)
; #define PG8_MMA(ai, bj, At, Bt) do { __builtin_amdgcn_s_setprio(1); _Pragma("unroll") for (int m = 0; m < 4; ++m) _Pragma("unroll") for (int n = 0; n < 2; ++n) _Pragma("unroll") for (int k = 0; k < 2; ++k) \
;         acc[ai][bj][m][n] = __builtin_amdgcn_mfma_f32_16x16x32_bf16(Bt[n][k], At[m][k], acc[ai][bj][m][n], 0, 0, 0); __builtin_amdgcn_s_setprio(0); } while (0)
; #define PG8_WAIT_V(n) asm volatile("s_waitcnt vmcnt(" #n ")" ::: "memory")
; #define PG8_WAIT_L(n) asm volatile("s_waitcnt lgkmcnt(" #n ")" ::: "memory")
; #define PG8_BAR __builtin_amdgcn_s_barrier()
; #define PG8_SCHED __builtin_amdgcn_sched_barrier(0)
; template <class Epi>
; __device__ __forceinline__ void gemm_phase(LAS unsigned char* lds, const Gemm g, const StaticOrder& S, const Epi& E) {
;     ...
;             const bool last = (t == nt - 2);
;             const char* a1 = cA + (size_t)(t + 1) * kstep;
;             const char* a2 = last ? nA : cA + (size_t)(t + 2) * kstep; const char* b2 = last ? nB : cB + (size_t)(t + 2) * kstep;
;             const char* a3 = a2 + kstep; const char* b3 = b2 + kstep;
;             PG8_LDB(B0, 0, 0); PG8_LDB(B1, 0, 1); PG8_SCHED; PG8_LDA(At, 0, 0); PG8_STAGE(PG8_SA(1, 1), a1 + hstepA, voffA);
;             PG8_WAIT_V(8); PG8_WAIT_L(0); PG8_BAR; PG8_MMA(0, 0, At, B0); PG8_MMA(0, 1, At, B1); PG8_BAR; PG8_SCHED;
;             PG8_LDA(At, 0, 1); PG8_STAGE(PG8_SB(0, 0), b2, voffB); PG8_STAGE(PG8_SB(0, 1), b2 + hstepB, voffB); PG8_STAGE(PG8_SA(0, 0), a2, voffA);
;             PG8_WAIT_V(8); PG8_WAIT_L(0); PG8_BAR; PG8_MMA(1, 0, At, B0); PG8_MMA(1, 1, At, B1); PG8_BAR; PG8_SCHED;
.LBB0_444:
	s_add_i32 s66, s28, 2
	s_add_u32 s8, s4, 0x100
	s_addc_u32 s9, s5, 0
	s_add_i32 vcc_lo, 0, 0x10000
	s_cmp_eq_u32 s65, s28
	s_cselect_b32 s57, s53, s9
	s_cselect_b32 s56, s52, s8
	v_add_u32_e32 v152, vcc_lo, v175
	s_cselect_b32 s29, s11, s59
	s_cselect_b32 s28, s51, s58
	s_add_i32 vcc_hi, 0, 0x14000
	ds_read_b128 v[140:143], v152
	ds_read_b128 v[144:147], v152 offset:1024
	ds_read_b128 v[148:151], v152 offset:2048
	ds_read_b128 v[166:169], v152 offset:3072
	v_add_u32_e32 v152, vcc_hi, v175
	ds_read_b128 v[170:173], v152
	ds_read_b128 v[178:181], v152 offset:1024
	ds_read_b128 v[182:185], v152 offset:2048
	ds_read_b128 v[186:189], v152 offset:3072
	v_lshl_add_u64 v[152:153], s[4:5], 0, v[138:139]
	s_add_i32 m0, s60, 0xc000
	ds_read_b128 v[190:193], v176
	ds_read_b128 v[194:197], v176 offset:1024
	ds_read_b128 v[198:201], v176 offset:2048
	ds_read_b128 v[224:227], v176 offset:3072
	ds_read_b128 v[228:231], v176 offset:4096
	ds_read_b128 v[232:235], v176 offset:5120
	ds_read_b128 v[236:239], v176 offset:6144
	ds_read_b128 v[240:243], v176 offset:7168
	global_load_lds_dwordx4 v[152:153], off
	v_lshl_add_u64 v[152:153], s[4:5], 0, v[136:137]
	s_add_i32 m0, s60, 0xe000
	s_nop 0
	global_load_lds_dwordx4 v[152:153], off
	s_waitcnt vmcnt(8)
	s_waitcnt lgkmcnt(0)
	s_barrier
	s_setprio 1
	s_waitcnt lgkmcnt(0)
	v_mfma_f32_16x16x32_bf16 v[126:129], v[140:143], v[190:193], v[126:129]
	v_mfma_f32_16x16x32_bf16 v[122:125], v[148:151], v[190:193], v[122:125]
	v_mfma_f32_16x16x32_bf16 v[118:121], v[140:143], v[198:201], v[118:121]
	v_mfma_f32_16x16x32_bf16 v[114:117], v[148:151], v[198:201], v[114:117]
	v_mfma_f32_16x16x32_bf16 v[110:113], v[140:143], v[228:231], v[110:113]
	v_mfma_f32_16x16x32_bf16 v[106:109], v[148:151], v[228:231], v[106:109]
	v_mfma_f32_16x16x32_bf16 v[102:105], v[140:143], v[236:239], v[102:105]
	v_mfma_f32_16x16x32_bf16 v[98:101], v[148:151], v[236:239], v[98:101]
	s_setprio 0
	s_setprio 1
	v_mfma_f32_16x16x32_bf16 v[126:129], v[144:147], v[194:197], v[126:129]
	v_mfma_f32_16x16x32_bf16 v[122:125], v[166:169], v[194:197], v[122:125]
	v_mfma_f32_16x16x32_bf16 v[118:121], v[144:147], v[224:227], v[118:121]
	v_mfma_f32_16x16x32_bf16 v[114:117], v[166:169], v[224:227], v[114:117]
	v_mfma_f32_16x16x32_bf16 v[110:113], v[144:147], v[232:235], v[110:113]
	v_mfma_f32_16x16x32_bf16 v[106:109], v[166:169], v[232:235], v[106:109]
	v_mfma_f32_16x16x32_bf16 v[102:105], v[144:147], v[240:243], v[102:105]
	v_mfma_f32_16x16x32_bf16 v[98:101], v[166:169], v[240:243], v[98:101]
	s_setprio 0
	s_setprio 1
	v_mfma_f32_16x16x32_bf16 v[62:65], v[170:173], v[190:193], v[62:65]
	v_mfma_f32_16x16x32_bf16 v[58:61], v[182:185], v[190:193], v[58:61]
	v_mfma_f32_16x16x32_bf16 v[54:57], v[170:173], v[198:201], v[54:57]
	v_mfma_f32_16x16x32_bf16 v[50:53], v[182:185], v[198:201], v[50:53]
	v_mfma_f32_16x16x32_bf16 v[46:49], v[170:173], v[228:231], v[46:49]
	v_mfma_f32_16x16x32_bf16 v[42:45], v[182:185], v[228:231], v[42:45]
	v_mfma_f32_16x16x32_bf16 v[38:41], v[170:173], v[236:239], v[38:41]
	v_mfma_f32_16x16x32_bf16 v[34:37], v[182:185], v[236:239], v[34:37]
	s_setprio 0
	s_setprio 1
	v_mfma_f32_16x16x32_bf16 v[62:65], v[178:181], v[194:197], v[62:65]
	v_mfma_f32_16x16x32_bf16 v[58:61], v[186:189], v[194:197], v[58:61]
	v_mfma_f32_16x16x32_bf16 v[54:57], v[178:181], v[224:227], v[54:57]
	v_mfma_f32_16x16x32_bf16 v[50:53], v[186:189], v[224:227], v[50:53]
	v_mfma_f32_16x16x32_bf16 v[46:49], v[178:181], v[232:235], v[46:49]
	v_mfma_f32_16x16x32_bf16 v[42:45], v[186:189], v[232:235], v[42:45]
	v_mfma_f32_16x16x32_bf16 v[38:41], v[178:181], v[240:243], v[38:41]
	v_mfma_f32_16x16x32_bf16 v[34:37], v[186:189], v[240:243], v[34:37]
	s_setprio 0
	s_barrier
	s_add_i32 s4, vcc_lo, s39
	v_lshl_add_u64 v[152:153], s[28:29], 0, v[0:1]
	s_mov_b32 m0, s4
	ds_read_b128 v[190:193], v176 offset:16384
	ds_read_b128 v[194:197], v176 offset:17408
	ds_read_b128 v[198:201], v176 offset:18432
	ds_read_b128 v[224:227], v176 offset:19456
	ds_read_b128 v[228:231], v176 offset:20480
	ds_read_b128 v[232:235], v176 offset:21504
	ds_read_b128 v[236:239], v176 offset:22528
	ds_read_b128 v[240:243], v176 offset:23552
	global_load_lds_dwordx4 v[152:153], off
	s_add_i32 m0, s4, 0x2000
	s_add_u32 s4, s28, 0x10000
	v_lshl_add_u64 v[202:203], s[28:29], 0, v[134:135]
	s_addc_u32 s5, s29, 0
	s_add_i32 vcc_lo, vcc_hi, s39
	global_load_lds_dwordx4 v[202:203], off
	v_lshl_add_u64 v[244:245], s[4:5], 0, v[0:1]
	s_mov_b32 m0, vcc_lo
	v_lshl_add_u64 v[246:247], s[56:57], 0, v[132:133]
	global_load_lds_dwordx4 v[244:245], off
	v_lshl_add_u64 v[244:245], s[4:5], 0, v[134:135]
	s_add_i32 m0, vcc_lo, 0x2000
	s_nop 0
	global_load_lds_dwordx4 v[244:245], off
	v_lshl_add_u64 v[244:245], s[56:57], 0, v[130:131]
	s_mov_b32 m0, s60
	s_nop 0
	global_load_lds_dwordx4 v[244:245], off
	s_mov_b32 m0, s61
	s_nop 0
	global_load_lds_dwordx4 v[246:247], off
	s_waitcnt vmcnt(8)
	s_waitcnt lgkmcnt(0)
	s_barrier
; #define PG8_STAGE(bufoff, gbase, voff) do { _Pragma("unroll") for (int _i = 0; _i < 2; ++_i) \
;         __builtin_amdgcn_global_load_lds((const unsigned*)((const char*)(gbase) + (voff)[_i]), (LAS unsigned*)(lds + (bufoff) + ldsw + _i * 8192), 16, 0, 0); } while (0)
; #define PG8_LDA(dst, b, h) do { _Pragma("unroll") for (int m = 0; m < 4; ++m) _Pragma("unroll") for (int k = 0; k < 2; ++k) dst[m][k] = *(const LAS bf16x8*)(lds + PG8_SA(b, h) + aoff + m * 2048 + k * 1024); } while (0)
; #define PG8_LDB(dst, b, h) do { _Pragma("unroll") for (int n = 0; n < 2; ++n) _Pragma("unroll") for (int k = 0; k < 2; ++k) dst[n][k] = *(const LAS bf16x8*)(lds + PG8_SB(b, h) + boff + n * 2048 + k * 1024); } while (0)
; #define PG8_MMA(ai, bj, At, Bt) do { __builtin_amdgcn_s_setprio(1); _Pragma("unroll") for (int m = 0; m < 4; ++m) _Pragma("unroll") for (int n = 0; n < 2; ++n) _Pragma("unroll") for (int k = 0; k < 2; ++k) \
;         acc[ai][bj][m][n] = __builtin_amdgcn_mfma_f32_16x16x32_bf16(Bt[n][k], At[m][k], acc[ai][bj][m][n], 0, 0, 0); __builtin_amdgcn_s_setprio(0); } while (0)
; #define PG8_WAIT_V(n) asm volatile("s_waitcnt vmcnt(" #n ")" ::: "memory")
; #define PG8_WAIT_L(n) asm volatile("s_waitcnt lgkmcnt(" #n ")" ::: "memory")
; #define PG8_BAR __builtin_amdgcn_s_barrier()
; #define PG8_SCHED __builtin_amdgcn_sched_barrier(0)
; template <class Epi>
; __device__ __forceinline__ void gemm_phase(LAS unsigned char* lds, const Gemm g, const StaticOrder& S, const Epi& E) {
;     ...
;             PG8_WAIT_V(8); PG8_WAIT_L(0); PG8_BAR; PG8_MMA(1, 0, At, B0); PG8_MMA(1, 1, At, B1); PG8_BAR; PG8_SCHED;
;             PG8_LDB(B0, 1, 0); PG8_LDB(B1, 1, 1); PG8_SCHED; PG8_LDA(At, 1, 0); PG8_STAGE(PG8_SA(0, 1), a2 + hstepA, voffA);
;             PG8_WAIT_V(8); PG8_WAIT_L(0); PG8_BAR; PG8_MMA(0, 0, At, B0); PG8_MMA(0, 1, At, B1); PG8_BAR; PG8_SCHED;
	s_setprio 1
	s_waitcnt lgkmcnt(0)
	v_mfma_f32_16x16x32_bf16 v[94:97], v[140:143], v[190:193], v[94:97]
	v_mfma_f32_16x16x32_bf16 v[90:93], v[148:151], v[190:193], v[90:93]
	v_mfma_f32_16x16x32_bf16 v[86:89], v[140:143], v[198:201], v[86:89]
	v_mfma_f32_16x16x32_bf16 v[82:85], v[148:151], v[198:201], v[82:85]
	v_mfma_f32_16x16x32_bf16 v[78:81], v[140:143], v[228:231], v[78:81]
	v_mfma_f32_16x16x32_bf16 v[74:77], v[148:151], v[228:231], v[74:77]
	v_mfma_f32_16x16x32_bf16 v[70:73], v[140:143], v[236:239], v[70:73]
	v_mfma_f32_16x16x32_bf16 v[66:69], v[148:151], v[236:239], v[66:69]
	s_setprio 0
	s_setprio 1
	v_mfma_f32_16x16x32_bf16 v[94:97], v[144:147], v[194:197], v[94:97]
	v_mfma_f32_16x16x32_bf16 v[90:93], v[166:169], v[194:197], v[90:93]
	v_mfma_f32_16x16x32_bf16 v[86:89], v[144:147], v[224:227], v[86:89]
	v_mfma_f32_16x16x32_bf16 v[82:85], v[166:169], v[224:227], v[82:85]
	v_mfma_f32_16x16x32_bf16 v[78:81], v[144:147], v[232:235], v[78:81]
	v_mfma_f32_16x16x32_bf16 v[74:77], v[166:169], v[232:235], v[74:77]
	v_mfma_f32_16x16x32_bf16 v[70:73], v[144:147], v[240:243], v[70:73]
	v_mfma_f32_16x16x32_bf16 v[66:69], v[166:169], v[240:243], v[66:69]
	s_setprio 0
	s_setprio 1
	v_mfma_f32_16x16x32_bf16 v[30:33], v[170:173], v[190:193], v[30:33]
	v_mfma_f32_16x16x32_bf16 v[26:29], v[182:185], v[190:193], v[26:29]
	v_mfma_f32_16x16x32_bf16 v[22:25], v[170:173], v[198:201], v[22:25]
	v_mfma_f32_16x16x32_bf16 v[18:21], v[182:185], v[198:201], v[18:21]
	v_mfma_f32_16x16x32_bf16 v[14:17], v[170:173], v[228:231], v[14:17]
	v_mfma_f32_16x16x32_bf16 v[10:13], v[182:185], v[228:231], v[10:13]
	v_mfma_f32_16x16x32_bf16 v[6:9], v[170:173], v[236:239], v[6:9]
	v_mfma_f32_16x16x32_bf16 v[2:5], v[182:185], v[236:239], v[2:5]
	s_setprio 0
	s_setprio 1
	v_mfma_f32_16x16x32_bf16 v[30:33], v[178:181], v[194:197], v[30:33]
	v_mfma_f32_16x16x32_bf16 v[26:29], v[186:189], v[194:197], v[26:29]
	v_mfma_f32_16x16x32_bf16 v[22:25], v[178:181], v[224:227], v[22:25]
	v_mfma_f32_16x16x32_bf16 v[18:21], v[186:189], v[224:227], v[18:21]
	v_mfma_f32_16x16x32_bf16 v[14:17], v[178:181], v[232:235], v[14:17]
	v_mfma_f32_16x16x32_bf16 v[10:13], v[186:189], v[232:235], v[10:13]
	v_mfma_f32_16x16x32_bf16 v[6:9], v[178:181], v[240:243], v[6:9]
	v_mfma_f32_16x16x32_bf16 v[2:5], v[186:189], v[240:243], v[2:5]
	s_setprio 0
	s_barrier
	s_add_i32 vcc_lo, 0, 0x18000
	s_add_i32 vcc_hi, 0, 0x1c000
	v_add_u32_e32 v166, vcc_lo, v175
	v_add_u32_e32 v177, vcc_hi, v175
	ds_read_b128 v[140:143], v166
	ds_read_b128 v[144:147], v166 offset:1024
	ds_read_b128 v[148:151], v166 offset:2048
	ds_read_b128 v[166:169], v166 offset:3072
	ds_read_b128 v[170:173], v177
	ds_read_b128 v[178:181], v177 offset:1024
	ds_read_b128 v[182:185], v177 offset:2048
	ds_read_b128 v[186:189], v177 offset:3072
	s_add_u32 s4, s56, 0xc0000
	s_addc_u32 s5, s57, 0
	s_mov_b32 m0, s62
	v_lshl_add_u64 v[248:249], s[4:5], 0, v[130:131]
	ds_read_b128 v[190:193], v176 offset:32768
	ds_read_b128 v[194:197], v176 offset:33792
	ds_read_b128 v[198:201], v176 offset:34816
	ds_read_b128 v[224:227], v176 offset:35840
	ds_read_b128 v[228:231], v176 offset:36864
	ds_read_b128 v[232:235], v176 offset:37888
	ds_read_b128 v[236:239], v176 offset:38912
	ds_read_b128 v[240:243], v176 offset:39936
	global_load_lds_dwordx4 v[248:249], off
	v_lshl_add_u64 v[248:249], s[4:5], 0, v[132:133]
	s_mov_b32 m0, s63
	s_nop 0
	global_load_lds_dwordx4 v[248:249], off
	s_waitcnt vmcnt(8)
	s_waitcnt lgkmcnt(0)
	s_barrier
	s_setprio 1
	s_waitcnt lgkmcnt(0)
	v_mfma_f32_16x16x32_bf16 v[126:129], v[140:143], v[190:193], v[126:129]
	v_mfma_f32_16x16x32_bf16 v[122:125], v[148:151], v[190:193], v[122:125]
	v_mfma_f32_16x16x32_bf16 v[118:121], v[140:143], v[198:201], v[118:121]
	v_mfma_f32_16x16x32_bf16 v[114:117], v[148:151], v[198:201], v[114:117]
	v_mfma_f32_16x16x32_bf16 v[110:113], v[140:143], v[228:231], v[110:113]
	v_mfma_f32_16x16x32_bf16 v[106:109], v[148:151], v[228:231], v[106:109]
	v_mfma_f32_16x16x32_bf16 v[102:105], v[140:143], v[236:239], v[102:105]
	v_mfma_f32_16x16x32_bf16 v[98:101], v[148:151], v[236:239], v[98:101]
	s_setprio 0
	s_setprio 1
	v_mfma_f32_16x16x32_bf16 v[126:129], v[144:147], v[194:197], v[126:129]
	v_mfma_f32_16x16x32_bf16 v[122:125], v[166:169], v[194:197], v[122:125]
	v_mfma_f32_16x16x32_bf16 v[118:121], v[144:147], v[224:227], v[118:121]
	v_mfma_f32_16x16x32_bf16 v[114:117], v[166:169], v[224:227], v[114:117]
	v_mfma_f32_16x16x32_bf16 v[110:113], v[144:147], v[232:235], v[110:113]
	v_mfma_f32_16x16x32_bf16 v[106:109], v[166:169], v[232:235], v[106:109]
	v_mfma_f32_16x16x32_bf16 v[102:105], v[144:147], v[240:243], v[102:105]
	v_mfma_f32_16x16x32_bf16 v[98:101], v[166:169], v[240:243], v[98:101]
	s_setprio 0
	s_setprio 1
	v_mfma_f32_16x16x32_bf16 v[62:65], v[170:173], v[190:193], v[62:65]
	v_mfma_f32_16x16x32_bf16 v[58:61], v[182:185], v[190:193], v[58:61]
	v_mfma_f32_16x16x32_bf16 v[54:57], v[170:173], v[198:201], v[54:57]
	v_mfma_f32_16x16x32_bf16 v[50:53], v[182:185], v[198:201], v[50:53]
	v_mfma_f32_16x16x32_bf16 v[46:49], v[170:173], v[228:231], v[46:49]
	v_mfma_f32_16x16x32_bf16 v[42:45], v[182:185], v[228:231], v[42:45]
	v_mfma_f32_16x16x32_bf16 v[38:41], v[170:173], v[236:239], v[38:41]
	v_mfma_f32_16x16x32_bf16 v[34:37], v[182:185], v[236:239], v[34:37]
	s_setprio 0
	s_setprio 1
	v_mfma_f32_16x16x32_bf16 v[62:65], v[178:181], v[194:197], v[62:65]
	v_mfma_f32_16x16x32_bf16 v[58:61], v[186:189], v[194:197], v[58:61]
	v_mfma_f32_16x16x32_bf16 v[54:57], v[178:181], v[224:227], v[54:57]
	v_mfma_f32_16x16x32_bf16 v[50:53], v[186:189], v[224:227], v[50:53]
	v_mfma_f32_16x16x32_bf16 v[46:49], v[178:181], v[232:235], v[46:49]
	v_mfma_f32_16x16x32_bf16 v[42:45], v[186:189], v[232:235], v[42:45]
	v_mfma_f32_16x16x32_bf16 v[38:41], v[178:181], v[240:243], v[38:41]
	v_mfma_f32_16x16x32_bf16 v[34:37], v[186:189], v[240:243], v[34:37]
	s_setprio 0
	s_barrier
; #define PG8_STAGE(bufoff, gbase, voff) do { _Pragma("unroll") for (int _i = 0; _i < 2; ++_i) \
;         __builtin_amdgcn_global_load_lds((const unsigned*)((const char*)(gbase) + (voff)[_i]), (LAS unsigned*)(lds + (bufoff) + ldsw + _i * 8192), 16, 0, 0); } while (0)
; #define PG8_LDA(dst, b, h) do { _Pragma("unroll") for (int m = 0; m < 4; ++m) _Pragma("unroll") for (int k = 0; k < 2; ++k) dst[m][k] = *(const LAS bf16x8*)(lds + PG8_SA(b, h) + aoff + m * 2048 + k * 1024); } while (0)
; #define PG8_MMA(ai, bj, At, Bt) do { __builtin_amdgcn_s_setprio(1); _Pragma("unroll") for (int m = 0; m < 4; ++m) _Pragma("unroll") for (int n = 0; n < 2; ++n) _Pragma("unroll") for (int k = 0; k < 2; ++k) \
;         acc[ai][bj][m][n] = __builtin_amdgcn_mfma_f32_16x16x32_bf16(Bt[n][k], At[m][k], acc[ai][bj][m][n], 0, 0, 0); __builtin_amdgcn_s_setprio(0); } while (0)
; #define PG8_WAIT_V(n) asm volatile("s_waitcnt vmcnt(" #n ")" ::: "memory")
; #define PG8_WAIT_L(n) asm volatile("s_waitcnt lgkmcnt(" #n ")" ::: "memory")
; #define PG8_BAR __builtin_amdgcn_s_barrier()
; #define PG8_SCHED __builtin_amdgcn_sched_barrier(0)
; template <class Epi>
; __device__ __forceinline__ void gemm_phase(LAS unsigned char* lds, const Gemm g, const StaticOrder& S, const Epi& E) {
;     ...
;             PG8_LDA(At, 1, 1); PG8_STAGE(PG8_SB(1, 0), b3, voffB); PG8_STAGE(PG8_SB(1, 1), b3 + hstepB, voffB); PG8_STAGE(PG8_SA(1, 0), a3, voffA);
;             PG8_WAIT_V(8); PG8_WAIT_L(0); PG8_BAR; PG8_MMA(1, 0, At, B0); PG8_MMA(1, 1, At, B1); PG8_BAR; PG8_SCHED;
;         }
	s_add_i32 s4, vcc_lo, s39
	v_lshl_add_u64 v[152:153], v[152:153], 0, s[74:75]
	s_mov_b32 m0, s4
	ds_read_b128 v[190:193], v176 offset:49152
	ds_read_b128 v[194:197], v176 offset:50176
	ds_read_b128 v[198:201], v176 offset:51200
	ds_read_b128 v[224:227], v176 offset:52224
	ds_read_b128 v[228:231], v176 offset:53248
	ds_read_b128 v[232:235], v176 offset:54272
	ds_read_b128 v[236:239], v176 offset:55296
	ds_read_b128 v[240:243], v176 offset:56320
	global_load_lds_dwordx4 v[152:153], off
	s_add_i32 m0, s4, 0x2000
	s_add_u32 s4, s28, 0x10080
	v_lshl_add_u64 v[152:153], v[202:203], 0, s[74:75]
	s_addc_u32 s5, s29, 0
	s_add_i32 s28, vcc_hi, s39
	global_load_lds_dwordx4 v[152:153], off
	v_lshl_add_u64 v[152:153], s[4:5], 0, v[0:1]
	s_mov_b32 m0, s28
	s_nop 0
	global_load_lds_dwordx4 v[152:153], off
	v_lshl_add_u64 v[152:153], s[4:5], 0, v[134:135]
	s_add_i32 m0, s28, 0x2000
	s_nop 0
	global_load_lds_dwordx4 v[152:153], off
	v_lshl_add_u64 v[152:153], v[244:245], 0, s[74:75]
	s_mov_b32 m0, s18
	s_nop 0
	global_load_lds_dwordx4 v[152:153], off
	v_lshl_add_u64 v[152:153], v[246:247], 0, s[74:75]
	s_mov_b32 m0, s19
	s_nop 0
	global_load_lds_dwordx4 v[152:153], off
	s_waitcnt vmcnt(8)
	s_waitcnt lgkmcnt(0)
	s_barrier
	s_setprio 1
	s_waitcnt lgkmcnt(0)
	v_mfma_f32_16x16x32_bf16 v[94:97], v[140:143], v[190:193], v[94:97]
	v_mfma_f32_16x16x32_bf16 v[90:93], v[148:151], v[190:193], v[90:93]
	v_mfma_f32_16x16x32_bf16 v[86:89], v[140:143], v[198:201], v[86:89]
	v_mfma_f32_16x16x32_bf16 v[82:85], v[148:151], v[198:201], v[82:85]
	v_mfma_f32_16x16x32_bf16 v[78:81], v[140:143], v[228:231], v[78:81]
	v_mfma_f32_16x16x32_bf16 v[74:77], v[148:151], v[228:231], v[74:77]
	v_mfma_f32_16x16x32_bf16 v[70:73], v[140:143], v[236:239], v[70:73]
	v_mfma_f32_16x16x32_bf16 v[66:69], v[148:151], v[236:239], v[66:69]
	s_setprio 0
	s_setprio 1
	v_mfma_f32_16x16x32_bf16 v[94:97], v[144:147], v[194:197], v[94:97]
	v_mfma_f32_16x16x32_bf16 v[90:93], v[166:169], v[194:197], v[90:93]
	v_mfma_f32_16x16x32_bf16 v[86:89], v[144:147], v[224:227], v[86:89]
	v_mfma_f32_16x16x32_bf16 v[82:85], v[166:169], v[224:227], v[82:85]
	v_mfma_f32_16x16x32_bf16 v[78:81], v[144:147], v[232:235], v[78:81]
	v_mfma_f32_16x16x32_bf16 v[74:77], v[166:169], v[232:235], v[74:77]
	v_mfma_f32_16x16x32_bf16 v[70:73], v[144:147], v[240:243], v[70:73]
	v_mfma_f32_16x16x32_bf16 v[66:69], v[166:169], v[240:243], v[66:69]
	s_setprio 0
	s_setprio 1
	v_mfma_f32_16x16x32_bf16 v[30:33], v[170:173], v[190:193], v[30:33]
	v_mfma_f32_16x16x32_bf16 v[26:29], v[182:185], v[190:193], v[26:29]
	v_mfma_f32_16x16x32_bf16 v[22:25], v[170:173], v[198:201], v[22:25]
	v_mfma_f32_16x16x32_bf16 v[18:21], v[182:185], v[198:201], v[18:21]
	v_mfma_f32_16x16x32_bf16 v[14:17], v[170:173], v[228:231], v[14:17]
	v_mfma_f32_16x16x32_bf16 v[10:13], v[182:185], v[228:231], v[10:13]
	v_mfma_f32_16x16x32_bf16 v[6:9], v[170:173], v[236:239], v[6:9]
	v_mfma_f32_16x16x32_bf16 v[2:5], v[182:185], v[236:239], v[2:5]
	s_setprio 0
	s_setprio 1
	v_mfma_f32_16x16x32_bf16 v[30:33], v[178:181], v[194:197], v[30:33]
	v_mfma_f32_16x16x32_bf16 v[26:29], v[186:189], v[194:197], v[26:29]
	v_mfma_f32_16x16x32_bf16 v[22:25], v[178:181], v[224:227], v[22:25]
	v_mfma_f32_16x16x32_bf16 v[18:21], v[186:189], v[224:227], v[18:21]
	v_mfma_f32_16x16x32_bf16 v[14:17], v[178:181], v[232:235], v[14:17]
	v_mfma_f32_16x16x32_bf16 v[10:13], v[186:189], v[232:235], v[10:13]
	v_mfma_f32_16x16x32_bf16 v[6:9], v[178:181], v[240:243], v[6:9]
	v_mfma_f32_16x16x32_bf16 v[2:5], v[186:189], v[240:243], v[2:5]
	s_setprio 0
	s_barrier
	s_add_u32 s58, s58, 0x100
	s_addc_u32 s59, s59, 0
	s_cmp_ge_i32 s66, s12
	s_mov_b64 s[4:5], s[8:9]
	s_mov_b32 s28, s66
	s_cbranch_scc0 .LBB0_444

; #define PG8_STAGE(bufoff, gbase, voff) do { _Pragma("unroll") for (int _i = 0; _i < 2; ++_i) \
;         __builtin_amdgcn_global_load_lds((const unsigned*)((const char*)(gbase) + (voff)[_i]), (LAS unsigned*)(lds + (bufoff) + ldsw + _i * 8192), 16, 0, 0); } while (0)
; #define PG8_LDA(dst, b, h) do { _Pragma("unroll") for (int m = 0; m < 4; ++m) _Pragma("unroll") for (int k = 0; k < 2; ++k) dst[m][k] = *(const LAS bf16x8*)(lds + PG8_SA(b, h) + aoff + m * 2048 + k * 1024); } while (0)
; #define PG8_LDB(dst, b, h) do { _Pragma("unroll") for (int n = 0; n < 2; ++n) _Pragma("unroll") for (int k = 0; k < 2; ++k) dst[n][k] = *(const LAS bf16x8*)(lds + PG8_SB(b, h) + boff + n * 2048 + k * 1024); } while (0)
; #define PG8_MMA(ai, bj, At, Bt) do { __builtin_amdgcn_s_setprio(1); _Pragma("unroll") for (int m = 0; m < 4; ++m) _Pragma("unroll") for (int n = 0; n < 2; ++n) _Pragma("unroll") for (int k = 0; k < 2; ++k) \
;         acc[ai][bj][m][n] = __builtin_amdgcn_mfma_f32_16x16x32_bf16(Bt[n][k], At[m][k], acc[ai][bj][m][n], 0, 0, 0); __builtin_amdgcn_s_setprio(0); } while (0)
; #define PG8_WAIT_V(n) asm volatile("s_waitcnt vmcnt(" #n ")" ::: "memory")
; #define PG8_WAIT_L(n) asm volatile("s_waitcnt lgkmcnt(" #n ")" ::: "memory")
; #define PG8_BAR __builtin_amdgcn_s_barrier()
; #define PG8_SCHED __builtin_amdgcn_sched_barrier(0)
; template <class Epi>
; __device__ __forceinline__ void gemm_phase(LAS unsigned char* lds, const Gemm g, const StaticOrder& S, const Epi& E) {
;     ...
;             const bool last = (t == nt - 2);
;             const char* a1 = cA + (size_t)(t + 1) * kstep;
;             const char* a2 = last ? nA : cA + (size_t)(t + 2) * kstep; const char* b2 = last ? nB : cB + (size_t)(t + 2) * kstep;
;             const char* a3 = a2 + kstep; const char* b3 = b2 + kstep;
;             PG8_LDB(B0, 0, 0); PG8_LDB(B1, 0, 1); PG8_SCHED; PG8_LDA(At, 0, 0); PG8_STAGE(PG8_SA(1, 1), a1 + hstepA, voffA);
;             PG8_WAIT_V(8); PG8_WAIT_L(0); PG8_BAR; PG8_MMA(0, 0, At, B0); PG8_MMA(0, 1, At, B1); PG8_BAR; PG8_SCHED;
;             PG8_LDA(At, 0, 1); PG8_STAGE(PG8_SB(0, 0), b2, voffB); PG8_STAGE(PG8_SB(0, 1), b2 + hstepB, voffB); PG8_STAGE(PG8_SA(0, 0), a2, voffA);
;             PG8_WAIT_V(8); PG8_WAIT_L(0); PG8_BAR; PG8_MMA(1, 0, At, B0); PG8_MMA(1, 1, At, B1); PG8_BAR; PG8_SCHED;
.LBB0_546:
	s_add_i32 s21, s10, 2
	s_add_u32 s11, s4, 0xfff80080
	s_addc_u32 s12, s5, -1
	s_add_i32 s36, 0, 0x10000
	s_cmp_eq_u32 s45, s10
	s_cselect_b32 s13, s9, s12
	s_cselect_b32 s12, s14, s11
	v_add_u32_e32 v152, s36, v171
	s_cselect_b32 s11, s15, s20
	s_cselect_b32 s10, s18, s19
	s_add_i32 s57, 0, 0x14000
	ds_read_b128 v[130:133], v152
	ds_read_b128 v[134:137], v152 offset:1024
	ds_read_b128 v[148:151], v152 offset:2048
	ds_read_b128 v[166:169], v152 offset:3072
	v_add_u32_e32 v152, s57, v171
	ds_read_b128 v[176:179], v152
	ds_read_b128 v[180:183], v152 offset:1024
	ds_read_b128 v[184:187], v152 offset:2048
	ds_read_b128 v[188:191], v152 offset:3072
	s_waitcnt lgkmcnt(0)
	v_lshl_add_u64 v[172:173], s[4:5], 0, v[146:147]
	s_add_i32 m0, s55, 0xc000
	ds_read_b128 v[192:195], v175
	ds_read_b128 v[196:199], v175 offset:1024
	ds_read_b128 v[200:203], v175 offset:2048
	ds_read_b128 v[224:227], v175 offset:3072
	ds_read_b128 v[228:231], v175 offset:4096
	ds_read_b128 v[232:235], v175 offset:5120
	ds_read_b128 v[236:239], v175 offset:6144
	ds_read_b128 v[240:243], v175 offset:7168
	global_load_lds_dwordx4 v[172:173], off
	v_lshl_add_u64 v[172:173], s[4:5], 0, v[144:145]
	s_add_i32 m0, s55, 0xe000
	s_nop 0
	global_load_lds_dwordx4 v[172:173], off
	s_waitcnt vmcnt(8)
	s_waitcnt lgkmcnt(0)
	s_barrier
	s_setprio 1
	s_waitcnt lgkmcnt(0)
	v_mfma_f32_16x16x32_bf16 v[122:125], v[130:133], v[192:195], v[122:125]
	v_mfma_f32_16x16x32_bf16 v[126:129], v[148:151], v[192:195], v[126:129]
	v_mfma_f32_16x16x32_bf16 v[110:113], v[130:133], v[200:203], v[110:113]
	v_mfma_f32_16x16x32_bf16 v[106:109], v[148:151], v[200:203], v[106:109]
	v_mfma_f32_16x16x32_bf16 v[94:97], v[130:133], v[228:231], v[94:97]
	v_mfma_f32_16x16x32_bf16 v[90:93], v[148:151], v[228:231], v[90:93]
	v_mfma_f32_16x16x32_bf16 v[78:81], v[130:133], v[236:239], v[78:81]
	v_mfma_f32_16x16x32_bf16 v[74:77], v[148:151], v[236:239], v[74:77]
	s_setprio 0
	s_setprio 1
	v_mfma_f32_16x16x32_bf16 v[122:125], v[134:137], v[196:199], v[122:125]
	v_mfma_f32_16x16x32_bf16 v[126:129], v[166:169], v[196:199], v[126:129]
	v_mfma_f32_16x16x32_bf16 v[110:113], v[134:137], v[224:227], v[110:113]
	v_mfma_f32_16x16x32_bf16 v[106:109], v[166:169], v[224:227], v[106:109]
	v_mfma_f32_16x16x32_bf16 v[94:97], v[134:137], v[232:235], v[94:97]
	v_mfma_f32_16x16x32_bf16 v[90:93], v[166:169], v[232:235], v[90:93]
	v_mfma_f32_16x16x32_bf16 v[78:81], v[134:137], v[240:243], v[78:81]
	v_mfma_f32_16x16x32_bf16 v[74:77], v[166:169], v[240:243], v[74:77]
	s_setprio 0
	s_setprio 1
	v_mfma_f32_16x16x32_bf16 v[118:121], v[176:179], v[192:195], v[118:121]
	v_mfma_f32_16x16x32_bf16 v[114:117], v[184:187], v[192:195], v[114:117]
	v_mfma_f32_16x16x32_bf16 v[102:105], v[176:179], v[200:203], v[102:105]
	v_mfma_f32_16x16x32_bf16 v[98:101], v[184:187], v[200:203], v[98:101]
	v_mfma_f32_16x16x32_bf16 v[86:89], v[176:179], v[228:231], v[86:89]
	v_mfma_f32_16x16x32_bf16 v[82:85], v[184:187], v[228:231], v[82:85]
	v_mfma_f32_16x16x32_bf16 v[70:73], v[176:179], v[236:239], v[70:73]
	v_mfma_f32_16x16x32_bf16 v[66:69], v[184:187], v[236:239], v[66:69]
	s_setprio 0
	s_setprio 1
	v_mfma_f32_16x16x32_bf16 v[118:121], v[180:183], v[196:199], v[118:121]
	v_mfma_f32_16x16x32_bf16 v[114:117], v[188:191], v[196:199], v[114:117]
	v_mfma_f32_16x16x32_bf16 v[102:105], v[180:183], v[224:227], v[102:105]
	v_mfma_f32_16x16x32_bf16 v[98:101], v[188:191], v[224:227], v[98:101]
	v_mfma_f32_16x16x32_bf16 v[86:89], v[180:183], v[232:235], v[86:89]
	v_mfma_f32_16x16x32_bf16 v[82:85], v[188:191], v[232:235], v[82:85]
	v_mfma_f32_16x16x32_bf16 v[70:73], v[180:183], v[240:243], v[70:73]
	v_mfma_f32_16x16x32_bf16 v[66:69], v[188:191], v[240:243], v[66:69]
	s_setprio 0
	s_barrier
	s_add_i32 s36, s36, s29
	v_lshl_add_u64 v[172:173], s[10:11], 0, v[0:1]
	s_mov_b32 m0, s36
	ds_read_b128 v[192:195], v175 offset:16384
	ds_read_b128 v[196:199], v175 offset:17408
	ds_read_b128 v[200:203], v175 offset:18432
	ds_read_b128 v[224:227], v175 offset:19456
	ds_read_b128 v[228:231], v175 offset:20480
	ds_read_b128 v[232:235], v175 offset:21504
	ds_read_b128 v[236:239], v175 offset:22528
	ds_read_b128 v[240:243], v175 offset:23552
	global_load_lds_dwordx4 v[172:173], off
	s_add_i32 m0, s36, 0x2000
	s_add_u32 s36, s10, 0x80000
	v_lshl_add_u64 v[244:245], s[10:11], 0, v[142:143]
	s_addc_u32 s37, s11, 0
	s_add_i32 s57, s57, s29
	global_load_lds_dwordx4 v[244:245], off
	v_lshl_add_u64 v[246:247], s[36:37], 0, v[0:1]
	s_mov_b32 m0, s57
	v_lshl_add_u64 v[248:249], s[12:13], 0, v[140:141]
	global_load_lds_dwordx4 v[246:247], off
	v_lshl_add_u64 v[246:247], s[36:37], 0, v[142:143]
	s_add_i32 m0, s57, 0x2000
	s_nop 0
	global_load_lds_dwordx4 v[246:247], off
	v_lshl_add_u64 v[246:247], s[12:13], 0, v[138:139]
	s_mov_b32 m0, s55
	s_nop 0
	global_load_lds_dwordx4 v[246:247], off
	s_mov_b32 m0, s64
	s_nop 0
	global_load_lds_dwordx4 v[248:249], off
	s_waitcnt vmcnt(8)
	s_waitcnt lgkmcnt(0)
	s_barrier
; #define PG8_STAGE(bufoff, gbase, voff) do { _Pragma("unroll") for (int _i = 0; _i < 2; ++_i) \
;         __builtin_amdgcn_global_load_lds((const unsigned*)((const char*)(gbase) + (voff)[_i]), (LAS unsigned*)(lds + (bufoff) + ldsw + _i * 8192), 16, 0, 0); } while (0)
; #define PG8_LDA(dst, b, h) do { _Pragma("unroll") for (int m = 0; m < 4; ++m) _Pragma("unroll") for (int k = 0; k < 2; ++k) dst[m][k] = *(const LAS bf16x8*)(lds + PG8_SA(b, h) + aoff + m * 2048 + k * 1024); } while (0)
; #define PG8_LDB(dst, b, h) do { _Pragma("unroll") for (int n = 0; n < 2; ++n) _Pragma("unroll") for (int k = 0; k < 2; ++k) dst[n][k] = *(const LAS bf16x8*)(lds + PG8_SB(b, h) + boff + n * 2048 + k * 1024); } while (0)
; #define PG8_MMA(ai, bj, At, Bt) do { __builtin_amdgcn_s_setprio(1); _Pragma("unroll") for (int m = 0; m < 4; ++m) _Pragma("unroll") for (int n = 0; n < 2; ++n) _Pragma("unroll") for (int k = 0; k < 2; ++k) \
;         acc[ai][bj][m][n] = __builtin_amdgcn_mfma_f32_16x16x32_bf16(Bt[n][k], At[m][k], acc[ai][bj][m][n], 0, 0, 0); __builtin_amdgcn_s_setprio(0); } while (0)
; #define PG8_WAIT_V(n) asm volatile("s_waitcnt vmcnt(" #n ")" ::: "memory")
; #define PG8_WAIT_L(n) asm volatile("s_waitcnt lgkmcnt(" #n ")" ::: "memory")
; #define PG8_BAR __builtin_amdgcn_s_barrier()
; #define PG8_SCHED __builtin_amdgcn_sched_barrier(0)
; template <class Epi>
; __device__ __forceinline__ void gemm_phase(LAS unsigned char* lds, const Gemm g, const StaticOrder& S, const Epi& E) {
;     ...
;             PG8_WAIT_V(8); PG8_WAIT_L(0); PG8_BAR; PG8_MMA(1, 0, At, B0); PG8_MMA(1, 1, At, B1); PG8_BAR; PG8_SCHED;
;             PG8_LDB(B0, 1, 0); PG8_LDB(B1, 1, 1); PG8_SCHED; PG8_LDA(At, 1, 0); PG8_STAGE(PG8_SA(0, 1), a2 + hstepA, voffA);
;             PG8_WAIT_V(8); PG8_WAIT_L(0); PG8_BAR; PG8_MMA(0, 0, At, B0); PG8_MMA(0, 1, At, B1); PG8_BAR; PG8_SCHED;
	s_setprio 1
	s_waitcnt lgkmcnt(0)
	v_mfma_f32_16x16x32_bf16 v[62:65], v[130:133], v[192:195], v[62:65]
	v_mfma_f32_16x16x32_bf16 v[58:61], v[148:151], v[192:195], v[58:61]
	v_mfma_f32_16x16x32_bf16 v[46:49], v[130:133], v[200:203], v[46:49]
	v_mfma_f32_16x16x32_bf16 v[42:45], v[148:151], v[200:203], v[42:45]
	v_mfma_f32_16x16x32_bf16 v[30:33], v[130:133], v[228:231], v[30:33]
	v_mfma_f32_16x16x32_bf16 v[26:29], v[148:151], v[228:231], v[26:29]
	v_mfma_f32_16x16x32_bf16 v[14:17], v[130:133], v[236:239], v[14:17]
	v_mfma_f32_16x16x32_bf16 v[10:13], v[148:151], v[236:239], v[10:13]
	s_setprio 0
	s_setprio 1
	v_mfma_f32_16x16x32_bf16 v[62:65], v[134:137], v[196:199], v[62:65]
	v_mfma_f32_16x16x32_bf16 v[58:61], v[166:169], v[196:199], v[58:61]
	v_mfma_f32_16x16x32_bf16 v[46:49], v[134:137], v[224:227], v[46:49]
	v_mfma_f32_16x16x32_bf16 v[42:45], v[166:169], v[224:227], v[42:45]
	v_mfma_f32_16x16x32_bf16 v[30:33], v[134:137], v[232:235], v[30:33]
	v_mfma_f32_16x16x32_bf16 v[26:29], v[166:169], v[232:235], v[26:29]
	v_mfma_f32_16x16x32_bf16 v[14:17], v[134:137], v[240:243], v[14:17]
	v_mfma_f32_16x16x32_bf16 v[10:13], v[166:169], v[240:243], v[10:13]
	s_setprio 0
	s_setprio 1
	v_mfma_f32_16x16x32_bf16 v[54:57], v[176:179], v[192:195], v[54:57]
	v_mfma_f32_16x16x32_bf16 v[50:53], v[184:187], v[192:195], v[50:53]
	v_mfma_f32_16x16x32_bf16 v[38:41], v[176:179], v[200:203], v[38:41]
	v_mfma_f32_16x16x32_bf16 v[34:37], v[184:187], v[200:203], v[34:37]
	v_mfma_f32_16x16x32_bf16 v[22:25], v[176:179], v[228:231], v[22:25]
	v_mfma_f32_16x16x32_bf16 v[18:21], v[184:187], v[228:231], v[18:21]
	v_mfma_f32_16x16x32_bf16 v[6:9], v[176:179], v[236:239], v[6:9]
	v_mfma_f32_16x16x32_bf16 v[2:5], v[184:187], v[236:239], v[2:5]
	s_setprio 0
	s_setprio 1
	v_mfma_f32_16x16x32_bf16 v[54:57], v[180:183], v[196:199], v[54:57]
	v_mfma_f32_16x16x32_bf16 v[50:53], v[188:191], v[196:199], v[50:53]
	v_mfma_f32_16x16x32_bf16 v[38:41], v[180:183], v[224:227], v[38:41]
	v_mfma_f32_16x16x32_bf16 v[34:37], v[188:191], v[224:227], v[34:37]
	v_mfma_f32_16x16x32_bf16 v[22:25], v[180:183], v[232:235], v[22:25]
	v_mfma_f32_16x16x32_bf16 v[18:21], v[188:191], v[232:235], v[18:21]
	v_mfma_f32_16x16x32_bf16 v[6:9], v[180:183], v[240:243], v[6:9]
	v_mfma_f32_16x16x32_bf16 v[2:5], v[188:191], v[240:243], v[2:5]
	s_setprio 0
	s_barrier
	s_add_i32 s36, 0, 0x18000
	v_add_u32_e32 v152, s36, v171
	s_add_i32 s37, 0, 0x1c000
	ds_read_b128 v[130:133], v152
	ds_read_b128 v[134:137], v152 offset:1024
	ds_read_b128 v[148:151], v152 offset:2048
	ds_read_b128 v[166:169], v152 offset:3072
	v_add_u32_e32 v152, s37, v171
	ds_read_b128 v[176:179], v152
	ds_read_b128 v[180:183], v152 offset:1024
	ds_read_b128 v[184:187], v152 offset:2048
	ds_read_b128 v[188:191], v152 offset:3072
	s_add_u32 s12, s12, 0x80000
	s_addc_u32 s13, s13, 0
	s_mov_b32 m0, s65
	v_lshl_add_u64 v[250:251], s[12:13], 0, v[138:139]
	ds_read_b128 v[192:195], v175 offset:32768
	ds_read_b128 v[196:199], v175 offset:33792
	ds_read_b128 v[200:203], v175 offset:34816
	ds_read_b128 v[224:227], v175 offset:35840
	ds_read_b128 v[228:231], v175 offset:36864
	ds_read_b128 v[232:235], v175 offset:37888
	ds_read_b128 v[236:239], v175 offset:38912
	ds_read_b128 v[240:243], v175 offset:39936
	global_load_lds_dwordx4 v[250:251], off
	v_lshl_add_u64 v[250:251], s[12:13], 0, v[140:141]
	s_mov_b32 m0, s93
	s_nop 0
	global_load_lds_dwordx4 v[250:251], off
	s_waitcnt vmcnt(8)
	s_waitcnt lgkmcnt(0)
	s_barrier
	s_setprio 1
	s_waitcnt lgkmcnt(0)
	v_mfma_f32_16x16x32_bf16 v[122:125], v[130:133], v[192:195], v[122:125]
	v_mfma_f32_16x16x32_bf16 v[126:129], v[148:151], v[192:195], v[126:129]
	v_mfma_f32_16x16x32_bf16 v[110:113], v[130:133], v[200:203], v[110:113]
	v_mfma_f32_16x16x32_bf16 v[106:109], v[148:151], v[200:203], v[106:109]
	v_mfma_f32_16x16x32_bf16 v[94:97], v[130:133], v[228:231], v[94:97]
	v_mfma_f32_16x16x32_bf16 v[90:93], v[148:151], v[228:231], v[90:93]
	v_mfma_f32_16x16x32_bf16 v[78:81], v[130:133], v[236:239], v[78:81]
	v_mfma_f32_16x16x32_bf16 v[74:77], v[148:151], v[236:239], v[74:77]
	s_setprio 0
	s_setprio 1
	v_mfma_f32_16x16x32_bf16 v[122:125], v[134:137], v[196:199], v[122:125]
	v_mfma_f32_16x16x32_bf16 v[126:129], v[166:169], v[196:199], v[126:129]
	v_mfma_f32_16x16x32_bf16 v[110:113], v[134:137], v[224:227], v[110:113]
	v_mfma_f32_16x16x32_bf16 v[106:109], v[166:169], v[224:227], v[106:109]
	v_mfma_f32_16x16x32_bf16 v[94:97], v[134:137], v[232:235], v[94:97]
	v_mfma_f32_16x16x32_bf16 v[90:93], v[166:169], v[232:235], v[90:93]
	v_mfma_f32_16x16x32_bf16 v[78:81], v[134:137], v[240:243], v[78:81]
	v_mfma_f32_16x16x32_bf16 v[74:77], v[166:169], v[240:243], v[74:77]
	s_setprio 0
	s_setprio 1
	v_mfma_f32_16x16x32_bf16 v[118:121], v[176:179], v[192:195], v[118:121]
	v_mfma_f32_16x16x32_bf16 v[114:117], v[184:187], v[192:195], v[114:117]
	v_mfma_f32_16x16x32_bf16 v[102:105], v[176:179], v[200:203], v[102:105]
	v_mfma_f32_16x16x32_bf16 v[98:101], v[184:187], v[200:203], v[98:101]
	v_mfma_f32_16x16x32_bf16 v[86:89], v[176:179], v[228:231], v[86:89]
	v_mfma_f32_16x16x32_bf16 v[82:85], v[184:187], v[228:231], v[82:85]
	v_mfma_f32_16x16x32_bf16 v[70:73], v[176:179], v[236:239], v[70:73]
	v_mfma_f32_16x16x32_bf16 v[66:69], v[184:187], v[236:239], v[66:69]
	s_setprio 0
	s_setprio 1
	v_mfma_f32_16x16x32_bf16 v[118:121], v[180:183], v[196:199], v[118:121]
	v_mfma_f32_16x16x32_bf16 v[114:117], v[188:191], v[196:199], v[114:117]
	v_mfma_f32_16x16x32_bf16 v[102:105], v[180:183], v[224:227], v[102:105]
	v_mfma_f32_16x16x32_bf16 v[98:101], v[188:191], v[224:227], v[98:101]
	v_mfma_f32_16x16x32_bf16 v[86:89], v[180:183], v[232:235], v[86:89]
	v_mfma_f32_16x16x32_bf16 v[82:85], v[188:191], v[232:235], v[82:85]
	v_mfma_f32_16x16x32_bf16 v[70:73], v[180:183], v[240:243], v[70:73]
	v_mfma_f32_16x16x32_bf16 v[66:69], v[188:191], v[240:243], v[66:69]
	s_setprio 0
	s_barrier
; #define PG8_STAGE(bufoff, gbase, voff) do { _Pragma("unroll") for (int _i = 0; _i < 2; ++_i) \
;         __builtin_amdgcn_global_load_lds((const unsigned*)((const char*)(gbase) + (voff)[_i]), (LAS unsigned*)(lds + (bufoff) + ldsw + _i * 8192), 16, 0, 0); } while (0)
; #define PG8_LDA(dst, b, h) do { _Pragma("unroll") for (int m = 0; m < 4; ++m) _Pragma("unroll") for (int k = 0; k < 2; ++k) dst[m][k] = *(const LAS bf16x8*)(lds + PG8_SA(b, h) + aoff + m * 2048 + k * 1024); } while (0)
; #define PG8_MMA(ai, bj, At, Bt) do { __builtin_amdgcn_s_setprio(1); _Pragma("unroll") for (int m = 0; m < 4; ++m) _Pragma("unroll") for (int n = 0; n < 2; ++n) _Pragma("unroll") for (int k = 0; k < 2; ++k) \
;         acc[ai][bj][m][n] = __builtin_amdgcn_mfma_f32_16x16x32_bf16(Bt[n][k], At[m][k], acc[ai][bj][m][n], 0, 0, 0); __builtin_amdgcn_s_setprio(0); } while (0)
; #define PG8_WAIT_V(n) asm volatile("s_waitcnt vmcnt(" #n ")" ::: "memory")
; #define PG8_WAIT_L(n) asm volatile("s_waitcnt lgkmcnt(" #n ")" ::: "memory")
; #define PG8_BAR __builtin_amdgcn_s_barrier()
; #define PG8_SCHED __builtin_amdgcn_sched_barrier(0)
; template <class Epi>
; __device__ __forceinline__ void gemm_phase(LAS unsigned char* lds, const Gemm g, const StaticOrder& S, const Epi& E) {
;     ...
;             PG8_LDA(At, 1, 1); PG8_STAGE(PG8_SB(1, 0), b3, voffB); PG8_STAGE(PG8_SB(1, 1), b3 + hstepB, voffB); PG8_STAGE(PG8_SA(1, 0), a3, voffA);
;             PG8_WAIT_V(8); PG8_WAIT_L(0); PG8_BAR; PG8_MMA(1, 0, At, B0); PG8_MMA(1, 1, At, B1); PG8_BAR; PG8_SCHED;
;         }
	s_add_i32 s12, s36, s29
	v_lshl_add_u64 v[172:173], v[172:173], 0, s[74:75]
	s_mov_b32 m0, s12
	ds_read_b128 v[192:195], v175 offset:49152
	ds_read_b128 v[196:199], v175 offset:50176
	ds_read_b128 v[200:203], v175 offset:51200
	ds_read_b128 v[224:227], v175 offset:52224
	ds_read_b128 v[228:231], v175 offset:53248
	ds_read_b128 v[232:235], v175 offset:54272
	ds_read_b128 v[236:239], v175 offset:55296
	ds_read_b128 v[240:243], v175 offset:56320
	global_load_lds_dwordx4 v[172:173], off
	s_add_i32 m0, s12, 0x2000
	s_add_u32 s10, s10, 0x80080
	v_lshl_add_u64 v[172:173], v[244:245], 0, s[74:75]
	s_addc_u32 s11, s11, 0
	s_add_i32 s12, s37, s29
	global_load_lds_dwordx4 v[172:173], off
	v_lshl_add_u64 v[172:173], s[10:11], 0, v[0:1]
	s_mov_b32 m0, s12
	s_nop 0
	global_load_lds_dwordx4 v[172:173], off
	v_lshl_add_u64 v[172:173], s[10:11], 0, v[142:143]
	s_add_i32 m0, s12, 0x2000
	s_nop 0
	global_load_lds_dwordx4 v[172:173], off
	v_lshl_add_u64 v[172:173], v[246:247], 0, s[74:75]
	s_mov_b32 m0, s38
	s_nop 0
	global_load_lds_dwordx4 v[172:173], off
	v_lshl_add_u64 v[172:173], v[248:249], 0, s[74:75]
	s_mov_b32 m0, s39
	s_nop 0
	global_load_lds_dwordx4 v[172:173], off
	s_waitcnt vmcnt(8)
	s_waitcnt lgkmcnt(0)
	s_barrier
	s_setprio 1
	s_waitcnt lgkmcnt(0)
	v_mfma_f32_16x16x32_bf16 v[62:65], v[130:133], v[192:195], v[62:65]
	v_mfma_f32_16x16x32_bf16 v[58:61], v[148:151], v[192:195], v[58:61]
	v_mfma_f32_16x16x32_bf16 v[46:49], v[130:133], v[200:203], v[46:49]
	v_mfma_f32_16x16x32_bf16 v[42:45], v[148:151], v[200:203], v[42:45]
	v_mfma_f32_16x16x32_bf16 v[30:33], v[130:133], v[228:231], v[30:33]
	v_mfma_f32_16x16x32_bf16 v[26:29], v[148:151], v[228:231], v[26:29]
	v_mfma_f32_16x16x32_bf16 v[14:17], v[130:133], v[236:239], v[14:17]
	v_mfma_f32_16x16x32_bf16 v[10:13], v[148:151], v[236:239], v[10:13]
	s_setprio 0
	s_setprio 1
	v_mfma_f32_16x16x32_bf16 v[62:65], v[134:137], v[196:199], v[62:65]
	v_mfma_f32_16x16x32_bf16 v[58:61], v[166:169], v[196:199], v[58:61]
	v_mfma_f32_16x16x32_bf16 v[46:49], v[134:137], v[224:227], v[46:49]
	v_mfma_f32_16x16x32_bf16 v[42:45], v[166:169], v[224:227], v[42:45]
	v_mfma_f32_16x16x32_bf16 v[30:33], v[134:137], v[232:235], v[30:33]
	v_mfma_f32_16x16x32_bf16 v[26:29], v[166:169], v[232:235], v[26:29]
	v_mfma_f32_16x16x32_bf16 v[14:17], v[134:137], v[240:243], v[14:17]
	v_mfma_f32_16x16x32_bf16 v[10:13], v[166:169], v[240:243], v[10:13]
	s_setprio 0
	s_setprio 1
	v_mfma_f32_16x16x32_bf16 v[54:57], v[176:179], v[192:195], v[54:57]
	v_mfma_f32_16x16x32_bf16 v[50:53], v[184:187], v[192:195], v[50:53]
	v_mfma_f32_16x16x32_bf16 v[38:41], v[176:179], v[200:203], v[38:41]
	v_mfma_f32_16x16x32_bf16 v[34:37], v[184:187], v[200:203], v[34:37]
	v_mfma_f32_16x16x32_bf16 v[22:25], v[176:179], v[228:231], v[22:25]
	v_mfma_f32_16x16x32_bf16 v[18:21], v[184:187], v[228:231], v[18:21]
	v_mfma_f32_16x16x32_bf16 v[6:9], v[176:179], v[236:239], v[6:9]
	v_mfma_f32_16x16x32_bf16 v[2:5], v[184:187], v[236:239], v[2:5]
	s_setprio 0
	s_setprio 1
	v_mfma_f32_16x16x32_bf16 v[54:57], v[180:183], v[196:199], v[54:57]
	v_mfma_f32_16x16x32_bf16 v[50:53], v[188:191], v[196:199], v[50:53]
	v_mfma_f32_16x16x32_bf16 v[38:41], v[180:183], v[224:227], v[38:41]
	v_mfma_f32_16x16x32_bf16 v[34:37], v[188:191], v[224:227], v[34:37]
	v_mfma_f32_16x16x32_bf16 v[22:25], v[180:183], v[232:235], v[22:25]
	v_mfma_f32_16x16x32_bf16 v[18:21], v[188:191], v[232:235], v[18:21]
	v_mfma_f32_16x16x32_bf16 v[6:9], v[180:183], v[240:243], v[6:9]
	v_mfma_f32_16x16x32_bf16 v[2:5], v[188:191], v[240:243], v[2:5]
	s_setprio 0
	s_barrier
	s_add_u32 s19, s19, 0x100
	s_addc_u32 s20, s20, 0
	s_add_u32 s4, s4, 0x100
	s_addc_u32 s5, s5, 0
	s_cmp_ge_i32 s21, s52
	s_mov_b32 s10, s21
	s_cbranch_scc0 .LBB0_546
	s_load_dwordx2 s[36:37], s[96:97], 0x8

; #define PG8_STAGE(bufoff, gbase, voff) do { _Pragma("unroll") for (int _i = 0; _i < 2; ++_i) \
;         __builtin_amdgcn_global_load_lds((const unsigned*)((const char*)(gbase) + (voff)[_i]), (LAS unsigned*)(lds + (bufoff) + ldsw + _i * 8192), 16, 0, 0); } while (0)
; #define PG8_LDA(dst, b, h) do { _Pragma("unroll") for (int m = 0; m < 4; ++m) _Pragma("unroll") for (int k = 0; k < 2; ++k) dst[m][k] = *(const LAS bf16x8*)(lds + PG8_SA(b, h) + aoff + m * 2048 + k * 1024); } while (0)
; #define PG8_LDB(dst, b, h) do { _Pragma("unroll") for (int n = 0; n < 2; ++n) _Pragma("unroll") for (int k = 0; k < 2; ++k) dst[n][k] = *(const LAS bf16x8*)(lds + PG8_SB(b, h) + boff + n * 2048 + k * 1024); } while (0)
; #define PG8_MMA(ai, bj, At, Bt) do { __builtin_amdgcn_s_setprio(1); _Pragma("unroll") for (int m = 0; m < 4; ++m) _Pragma("unroll") for (int n = 0; n < 2; ++n) _Pragma("unroll") for (int k = 0; k < 2; ++k) \
;         acc[ai][bj][m][n] = __builtin_amdgcn_mfma_f32_16x16x32_bf16(Bt[n][k], At[m][k], acc[ai][bj][m][n], 0, 0, 0); __builtin_amdgcn_s_setprio(0); } while (0)
; #define PG8_WAIT_V(n) asm volatile("s_waitcnt vmcnt(" #n ")" ::: "memory")
; #define PG8_WAIT_L(n) asm volatile("s_waitcnt lgkmcnt(" #n ")" ::: "memory")
; #define PG8_BAR __builtin_amdgcn_s_barrier()
; #define PG8_SCHED __builtin_amdgcn_sched_barrier(0)
; template <class Epi>
; __device__ __forceinline__ void gemm_phase(LAS unsigned char* lds, const Gemm g, const StaticOrder& S, const Epi& E) {
;     ...
;             const bool last = (t == nt - 2);
;             const char* a1 = cA + (size_t)(t + 1) * kstep;
;             const char* a2 = last ? nA : cA + (size_t)(t + 2) * kstep; const char* b2 = last ? nB : cB + (size_t)(t + 2) * kstep;
;             const char* a3 = a2 + kstep; const char* b3 = b2 + kstep;
;             PG8_LDB(B0, 0, 0); PG8_LDB(B1, 0, 1); PG8_SCHED; PG8_LDA(At, 0, 0); PG8_STAGE(PG8_SA(1, 1), a1 + hstepA, voffA);
;             PG8_WAIT_V(8); PG8_WAIT_L(0); PG8_BAR; PG8_MMA(0, 0, At, B0); PG8_MMA(0, 1, At, B1); PG8_BAR; PG8_SCHED;
;             PG8_LDA(At, 0, 1); PG8_STAGE(PG8_SB(0, 0), b2, voffB); PG8_STAGE(PG8_SB(0, 1), b2 + hstepB, voffB); PG8_STAGE(PG8_SA(0, 0), a2, voffA);
;             PG8_WAIT_V(8); PG8_WAIT_L(0); PG8_BAR; PG8_MMA(1, 0, At, B0); PG8_MMA(1, 1, At, B1); PG8_BAR; PG8_SCHED;
.LBB0_690:
	s_add_i32 s28, s8, 2
	s_add_u32 s29, s4, 0x80
	s_addc_u32 s9, s5, 0
	s_add_i32 s66, 0, 0x10000
	s_cmp_eq_u32 s55, s8
	s_cselect_b32 s9, s41, s9
	s_cselect_b32 s8, s40, s29
	s_cselect_b32 s65, s47, s63
	s_cselect_b32 s64, s46, s62
	s_add_i32 s29, 0, 0x14000
	v_add_u32_e32 v142, s66, v193
	v_add_u32_e32 v180, s29, v193
	ds_read_b128 v[130:133], v142
	ds_read_b128 v[134:137], v142 offset:1024
	ds_read_b128 v[138:141], v142 offset:2048
	ds_read_b128 v[142:145], v142 offset:3072
	ds_read_b128 v[146:149], v180
	ds_read_b128 v[150:153], v180 offset:1024
	ds_read_b128 v[176:179], v180 offset:2048
	ds_read_b128 v[180:183], v180 offset:3072
	v_lshl_add_u64 v[240:241], s[4:5], 0, v[174:175]
	s_add_i32 m0, s49, 0xc000
	ds_read_b128 v[184:187], v194
	ds_read_b128 v[188:191], v194 offset:1024
	ds_read_b128 v[196:199], v194 offset:2048
	ds_read_b128 v[200:203], v194 offset:3072
	ds_read_b128 v[224:227], v194 offset:4096
	ds_read_b128 v[228:231], v194 offset:5120
	ds_read_b128 v[232:235], v194 offset:6144
	ds_read_b128 v[236:239], v194 offset:7168
	global_load_lds_dwordx4 v[240:241], off
	v_lshl_add_u64 v[240:241], s[4:5], 0, v[172:173]
	s_add_i32 m0, s49, 0xe000
	s_nop 0
	global_load_lds_dwordx4 v[240:241], off
	s_waitcnt vmcnt(8)
	s_waitcnt lgkmcnt(0)
	s_barrier
	s_setprio 1
	s_waitcnt lgkmcnt(0)
	v_mfma_f32_16x16x32_bf16 v[126:129], v[130:133], v[184:187], v[126:129]
	v_mfma_f32_16x16x32_bf16 v[122:125], v[138:141], v[184:187], v[122:125]
	v_mfma_f32_16x16x32_bf16 v[110:113], v[130:133], v[196:199], v[110:113]
	v_mfma_f32_16x16x32_bf16 v[106:109], v[138:141], v[196:199], v[106:109]
	v_mfma_f32_16x16x32_bf16 v[94:97], v[130:133], v[224:227], v[94:97]
	v_mfma_f32_16x16x32_bf16 v[90:93], v[138:141], v[224:227], v[90:93]
	v_mfma_f32_16x16x32_bf16 v[78:81], v[130:133], v[232:235], v[78:81]
	v_mfma_f32_16x16x32_bf16 v[74:77], v[138:141], v[232:235], v[74:77]
	s_setprio 0
	s_setprio 1
	v_mfma_f32_16x16x32_bf16 v[126:129], v[134:137], v[188:191], v[126:129]
	v_mfma_f32_16x16x32_bf16 v[122:125], v[142:145], v[188:191], v[122:125]
	v_mfma_f32_16x16x32_bf16 v[110:113], v[134:137], v[200:203], v[110:113]
	v_mfma_f32_16x16x32_bf16 v[106:109], v[142:145], v[200:203], v[106:109]
	v_mfma_f32_16x16x32_bf16 v[94:97], v[134:137], v[228:231], v[94:97]
	v_mfma_f32_16x16x32_bf16 v[90:93], v[142:145], v[228:231], v[90:93]
	v_mfma_f32_16x16x32_bf16 v[78:81], v[134:137], v[236:239], v[78:81]
	v_mfma_f32_16x16x32_bf16 v[74:77], v[142:145], v[236:239], v[74:77]
	s_setprio 0
	s_setprio 1
	v_mfma_f32_16x16x32_bf16 v[118:121], v[146:149], v[184:187], v[118:121]
	v_mfma_f32_16x16x32_bf16 v[114:117], v[176:179], v[184:187], v[114:117]
	v_mfma_f32_16x16x32_bf16 v[102:105], v[146:149], v[196:199], v[102:105]
	v_mfma_f32_16x16x32_bf16 v[98:101], v[176:179], v[196:199], v[98:101]
	v_mfma_f32_16x16x32_bf16 v[86:89], v[146:149], v[224:227], v[86:89]
	v_mfma_f32_16x16x32_bf16 v[82:85], v[176:179], v[224:227], v[82:85]
	v_mfma_f32_16x16x32_bf16 v[70:73], v[146:149], v[232:235], v[70:73]
	v_mfma_f32_16x16x32_bf16 v[66:69], v[176:179], v[232:235], v[66:69]
	s_setprio 0
	s_setprio 1
	v_mfma_f32_16x16x32_bf16 v[118:121], v[150:153], v[188:191], v[118:121]
	v_mfma_f32_16x16x32_bf16 v[114:117], v[180:183], v[188:191], v[114:117]
	v_mfma_f32_16x16x32_bf16 v[102:105], v[150:153], v[200:203], v[102:105]
	v_mfma_f32_16x16x32_bf16 v[98:101], v[180:183], v[200:203], v[98:101]
	v_mfma_f32_16x16x32_bf16 v[86:89], v[150:153], v[228:231], v[86:89]
	v_mfma_f32_16x16x32_bf16 v[82:85], v[180:183], v[228:231], v[82:85]
	v_mfma_f32_16x16x32_bf16 v[70:73], v[150:153], v[236:239], v[70:73]
	v_mfma_f32_16x16x32_bf16 v[66:69], v[180:183], v[236:239], v[66:69]
	s_setprio 0
	s_barrier
	s_add_i32 s66, s66, s48
	v_lshl_add_u64 v[240:241], s[64:65], 0, v[0:1]
	s_mov_b32 m0, s66
	ds_read_b128 v[184:187], v194 offset:16384
	ds_read_b128 v[188:191], v194 offset:17408
	ds_read_b128 v[196:199], v194 offset:18432
	ds_read_b128 v[200:203], v194 offset:19456
	ds_read_b128 v[224:227], v194 offset:20480
	ds_read_b128 v[228:231], v194 offset:21504
	ds_read_b128 v[232:235], v194 offset:22528
	ds_read_b128 v[236:239], v194 offset:23552
	global_load_lds_dwordx4 v[240:241], off
	s_add_i32 m0, s66, 0x2000
	v_lshl_add_u64 v[242:243], s[64:65], 0, v[170:171]
	s_add_u32 s64, s64, s12
	s_addc_u32 s65, s65, 0
	s_add_i32 s29, s29, s48
	global_load_lds_dwordx4 v[242:243], off
	v_lshl_add_u64 v[244:245], s[64:65], 0, v[0:1]
	s_mov_b32 m0, s29
	v_lshl_add_u64 v[246:247], s[64:65], 0, v[170:171]
	global_load_lds_dwordx4 v[244:245], off
	s_add_i32 m0, s29, 0x2000
	v_lshl_add_u64 v[248:249], s[8:9], 0, v[166:167]
	global_load_lds_dwordx4 v[246:247], off
	s_mov_b32 m0, s49
	v_lshl_add_u64 v[250:251], s[8:9], 0, v[168:169]
	global_load_lds_dwordx4 v[248:249], off
	s_mov_b32 m0, s50
	s_nop 0
	global_load_lds_dwordx4 v[250:251], off
	s_waitcnt vmcnt(8)
	s_waitcnt lgkmcnt(0)
	s_barrier
; #define PG8_STAGE(bufoff, gbase, voff) do { _Pragma("unroll") for (int _i = 0; _i < 2; ++_i) \
;         __builtin_amdgcn_global_load_lds((const unsigned*)((const char*)(gbase) + (voff)[_i]), (LAS unsigned*)(lds + (bufoff) + ldsw + _i * 8192), 16, 0, 0); } while (0)
; #define PG8_LDA(dst, b, h) do { _Pragma("unroll") for (int m = 0; m < 4; ++m) _Pragma("unroll") for (int k = 0; k < 2; ++k) dst[m][k] = *(const LAS bf16x8*)(lds + PG8_SA(b, h) + aoff + m * 2048 + k * 1024); } while (0)
; #define PG8_LDB(dst, b, h) do { _Pragma("unroll") for (int n = 0; n < 2; ++n) _Pragma("unroll") for (int k = 0; k < 2; ++k) dst[n][k] = *(const LAS bf16x8*)(lds + PG8_SB(b, h) + boff + n * 2048 + k * 1024); } while (0)
; #define PG8_MMA(ai, bj, At, Bt) do { __builtin_amdgcn_s_setprio(1); _Pragma("unroll") for (int m = 0; m < 4; ++m) _Pragma("unroll") for (int n = 0; n < 2; ++n) _Pragma("unroll") for (int k = 0; k < 2; ++k) \
;         acc[ai][bj][m][n] = __builtin_amdgcn_mfma_f32_16x16x32_bf16(Bt[n][k], At[m][k], acc[ai][bj][m][n], 0, 0, 0); __builtin_amdgcn_s_setprio(0); } while (0)
; #define PG8_WAIT_V(n) asm volatile("s_waitcnt vmcnt(" #n ")" ::: "memory")
; #define PG8_WAIT_L(n) asm volatile("s_waitcnt lgkmcnt(" #n ")" ::: "memory")
; #define PG8_BAR __builtin_amdgcn_s_barrier()
; #define PG8_SCHED __builtin_amdgcn_sched_barrier(0)
; template <class Epi>
; __device__ __forceinline__ void gemm_phase(LAS unsigned char* lds, const Gemm g, const StaticOrder& S, const Epi& E) {
;     ...
;             PG8_WAIT_V(8); PG8_WAIT_L(0); PG8_BAR; PG8_MMA(1, 0, At, B0); PG8_MMA(1, 1, At, B1); PG8_BAR; PG8_SCHED;
;             PG8_LDB(B0, 1, 0); PG8_LDB(B1, 1, 1); PG8_SCHED; PG8_LDA(At, 1, 0); PG8_STAGE(PG8_SA(0, 1), a2 + hstepA, voffA);
;             PG8_WAIT_V(8); PG8_WAIT_L(0); PG8_BAR; PG8_MMA(0, 0, At, B0); PG8_MMA(0, 1, At, B1); PG8_BAR; PG8_SCHED;
	s_setprio 1
	s_waitcnt lgkmcnt(0)
	v_mfma_f32_16x16x32_bf16 v[62:65], v[130:133], v[184:187], v[62:65]
	v_mfma_f32_16x16x32_bf16 v[58:61], v[138:141], v[184:187], v[58:61]
	v_mfma_f32_16x16x32_bf16 v[46:49], v[130:133], v[196:199], v[46:49]
	v_mfma_f32_16x16x32_bf16 v[42:45], v[138:141], v[196:199], v[42:45]
	v_mfma_f32_16x16x32_bf16 v[30:33], v[130:133], v[224:227], v[30:33]
	v_mfma_f32_16x16x32_bf16 v[26:29], v[138:141], v[224:227], v[26:29]
	v_mfma_f32_16x16x32_bf16 v[14:17], v[130:133], v[232:235], v[14:17]
	v_mfma_f32_16x16x32_bf16 v[10:13], v[138:141], v[232:235], v[10:13]
	s_setprio 0
	s_setprio 1
	v_mfma_f32_16x16x32_bf16 v[62:65], v[134:137], v[188:191], v[62:65]
	v_mfma_f32_16x16x32_bf16 v[58:61], v[142:145], v[188:191], v[58:61]
	v_mfma_f32_16x16x32_bf16 v[46:49], v[134:137], v[200:203], v[46:49]
	v_mfma_f32_16x16x32_bf16 v[42:45], v[142:145], v[200:203], v[42:45]
	v_mfma_f32_16x16x32_bf16 v[30:33], v[134:137], v[228:231], v[30:33]
	v_mfma_f32_16x16x32_bf16 v[26:29], v[142:145], v[228:231], v[26:29]
	v_mfma_f32_16x16x32_bf16 v[14:17], v[134:137], v[236:239], v[14:17]
	v_mfma_f32_16x16x32_bf16 v[10:13], v[142:145], v[236:239], v[10:13]
	s_setprio 0
	s_setprio 1
	v_mfma_f32_16x16x32_bf16 v[54:57], v[146:149], v[184:187], v[54:57]
	v_mfma_f32_16x16x32_bf16 v[50:53], v[176:179], v[184:187], v[50:53]
	v_mfma_f32_16x16x32_bf16 v[38:41], v[146:149], v[196:199], v[38:41]
	v_mfma_f32_16x16x32_bf16 v[34:37], v[176:179], v[196:199], v[34:37]
	v_mfma_f32_16x16x32_bf16 v[22:25], v[146:149], v[224:227], v[22:25]
	v_mfma_f32_16x16x32_bf16 v[18:21], v[176:179], v[224:227], v[18:21]
	v_mfma_f32_16x16x32_bf16 v[6:9], v[146:149], v[232:235], v[6:9]
	v_mfma_f32_16x16x32_bf16 v[2:5], v[176:179], v[232:235], v[2:5]
	s_setprio 0
	s_setprio 1
	v_mfma_f32_16x16x32_bf16 v[54:57], v[150:153], v[188:191], v[54:57]
	v_mfma_f32_16x16x32_bf16 v[50:53], v[180:183], v[188:191], v[50:53]
	v_mfma_f32_16x16x32_bf16 v[38:41], v[150:153], v[200:203], v[38:41]
	v_mfma_f32_16x16x32_bf16 v[34:37], v[180:183], v[200:203], v[34:37]
	v_mfma_f32_16x16x32_bf16 v[22:25], v[150:153], v[228:231], v[22:25]
	v_mfma_f32_16x16x32_bf16 v[18:21], v[180:183], v[228:231], v[18:21]
	v_mfma_f32_16x16x32_bf16 v[6:9], v[150:153], v[236:239], v[6:9]
	v_mfma_f32_16x16x32_bf16 v[2:5], v[180:183], v[236:239], v[2:5]
	s_setprio 0
	s_barrier
	s_add_i32 s29, 0, 0x18000
	s_add_i32 s64, 0, 0x1c000
	v_add_u32_e32 v142, s29, v193
	v_add_u32_e32 v180, s64, v193
	ds_read_b128 v[130:133], v142
	ds_read_b128 v[134:137], v142 offset:1024
	ds_read_b128 v[138:141], v142 offset:2048
	ds_read_b128 v[142:145], v142 offset:3072
	ds_read_b128 v[146:149], v180
	ds_read_b128 v[150:153], v180 offset:1024
	ds_read_b128 v[176:179], v180 offset:2048
	ds_read_b128 v[180:183], v180 offset:3072
	s_add_u32 s8, s8, s12
	s_addc_u32 s9, s9, 0
	s_mov_b32 m0, s18
	v_lshl_add_u64 v[252:253], s[8:9], 0, v[166:167]
	ds_read_b128 v[184:187], v194 offset:32768
	ds_read_b128 v[188:191], v194 offset:33792
	ds_read_b128 v[196:199], v194 offset:34816
	ds_read_b128 v[200:203], v194 offset:35840
	ds_read_b128 v[224:227], v194 offset:36864
	ds_read_b128 v[228:231], v194 offset:37888
	ds_read_b128 v[232:235], v194 offset:38912
	ds_read_b128 v[236:239], v194 offset:39936
	global_load_lds_dwordx4 v[252:253], off
	v_lshl_add_u64 v[252:253], s[8:9], 0, v[168:169]
	s_mov_b32 m0, s19
	s_nop 0
	global_load_lds_dwordx4 v[252:253], off
	s_waitcnt vmcnt(8)
	s_waitcnt lgkmcnt(0)
	s_barrier
	s_setprio 1
	s_waitcnt lgkmcnt(0)
	v_mfma_f32_16x16x32_bf16 v[126:129], v[130:133], v[184:187], v[126:129]
	v_mfma_f32_16x16x32_bf16 v[122:125], v[138:141], v[184:187], v[122:125]
	v_mfma_f32_16x16x32_bf16 v[110:113], v[130:133], v[196:199], v[110:113]
	v_mfma_f32_16x16x32_bf16 v[106:109], v[138:141], v[196:199], v[106:109]
	v_mfma_f32_16x16x32_bf16 v[94:97], v[130:133], v[224:227], v[94:97]
	v_mfma_f32_16x16x32_bf16 v[90:93], v[138:141], v[224:227], v[90:93]
	v_mfma_f32_16x16x32_bf16 v[78:81], v[130:133], v[232:235], v[78:81]
	v_mfma_f32_16x16x32_bf16 v[74:77], v[138:141], v[232:235], v[74:77]
	s_setprio 0
	s_setprio 1
	v_mfma_f32_16x16x32_bf16 v[126:129], v[134:137], v[188:191], v[126:129]
	v_mfma_f32_16x16x32_bf16 v[122:125], v[142:145], v[188:191], v[122:125]
	v_mfma_f32_16x16x32_bf16 v[110:113], v[134:137], v[200:203], v[110:113]
	v_mfma_f32_16x16x32_bf16 v[106:109], v[142:145], v[200:203], v[106:109]
	v_mfma_f32_16x16x32_bf16 v[94:97], v[134:137], v[228:231], v[94:97]
	v_mfma_f32_16x16x32_bf16 v[90:93], v[142:145], v[228:231], v[90:93]
	v_mfma_f32_16x16x32_bf16 v[78:81], v[134:137], v[236:239], v[78:81]
	v_mfma_f32_16x16x32_bf16 v[74:77], v[142:145], v[236:239], v[74:77]
	s_setprio 0
	s_setprio 1
	v_mfma_f32_16x16x32_bf16 v[118:121], v[146:149], v[184:187], v[118:121]
	v_mfma_f32_16x16x32_bf16 v[114:117], v[176:179], v[184:187], v[114:117]
	v_mfma_f32_16x16x32_bf16 v[102:105], v[146:149], v[196:199], v[102:105]
	v_mfma_f32_16x16x32_bf16 v[98:101], v[176:179], v[196:199], v[98:101]
	v_mfma_f32_16x16x32_bf16 v[86:89], v[146:149], v[224:227], v[86:89]
	v_mfma_f32_16x16x32_bf16 v[82:85], v[176:179], v[224:227], v[82:85]
	v_mfma_f32_16x16x32_bf16 v[70:73], v[146:149], v[232:235], v[70:73]
	v_mfma_f32_16x16x32_bf16 v[66:69], v[176:179], v[232:235], v[66:69]
	s_setprio 0
	s_setprio 1
	v_mfma_f32_16x16x32_bf16 v[118:121], v[150:153], v[188:191], v[118:121]
	v_mfma_f32_16x16x32_bf16 v[114:117], v[180:183], v[188:191], v[114:117]
	v_mfma_f32_16x16x32_bf16 v[102:105], v[150:153], v[200:203], v[102:105]
	v_mfma_f32_16x16x32_bf16 v[98:101], v[180:183], v[200:203], v[98:101]
	v_mfma_f32_16x16x32_bf16 v[86:89], v[150:153], v[228:231], v[86:89]
	v_mfma_f32_16x16x32_bf16 v[82:85], v[180:183], v[228:231], v[82:85]
	v_mfma_f32_16x16x32_bf16 v[70:73], v[150:153], v[236:239], v[70:73]
	v_mfma_f32_16x16x32_bf16 v[66:69], v[180:183], v[236:239], v[66:69]
	s_setprio 0
	s_barrier
; #define PG8_STAGE(bufoff, gbase, voff) do { _Pragma("unroll") for (int _i = 0; _i < 2; ++_i) \
;         __builtin_amdgcn_global_load_lds((const unsigned*)((const char*)(gbase) + (voff)[_i]), (LAS unsigned*)(lds + (bufoff) + ldsw + _i * 8192), 16, 0, 0); } while (0)
; #define PG8_LDA(dst, b, h) do { _Pragma("unroll") for (int m = 0; m < 4; ++m) _Pragma("unroll") for (int k = 0; k < 2; ++k) dst[m][k] = *(const LAS bf16x8*)(lds + PG8_SA(b, h) + aoff + m * 2048 + k * 1024); } while (0)
; #define PG8_MMA(ai, bj, At, Bt) do { __builtin_amdgcn_s_setprio(1); _Pragma("unroll") for (int m = 0; m < 4; ++m) _Pragma("unroll") for (int n = 0; n < 2; ++n) _Pragma("unroll") for (int k = 0; k < 2; ++k) \
;         acc[ai][bj][m][n] = __builtin_amdgcn_mfma_f32_16x16x32_bf16(Bt[n][k], At[m][k], acc[ai][bj][m][n], 0, 0, 0); __builtin_amdgcn_s_setprio(0); } while (0)
; #define PG8_WAIT_V(n) asm volatile("s_waitcnt vmcnt(" #n ")" ::: "memory")
; #define PG8_WAIT_L(n) asm volatile("s_waitcnt lgkmcnt(" #n ")" ::: "memory")
; #define PG8_BAR __builtin_amdgcn_s_barrier()
; #define PG8_SCHED __builtin_amdgcn_sched_barrier(0)
; template <class Epi>
; __device__ __forceinline__ void gemm_phase(LAS unsigned char* lds, const Gemm g, const StaticOrder& S, const Epi& E) {
;     ...
;             PG8_LDA(At, 1, 1); PG8_STAGE(PG8_SB(1, 0), b3, voffB); PG8_STAGE(PG8_SB(1, 1), b3 + hstepB, voffB); PG8_STAGE(PG8_SA(1, 0), a3, voffA);
;             PG8_WAIT_V(8); PG8_WAIT_L(0); PG8_BAR; PG8_MMA(1, 0, At, B0); PG8_MMA(1, 1, At, B1); PG8_BAR; PG8_SCHED;
;         }
	s_add_i32 s8, s29, s48
	v_lshl_add_u64 v[240:241], v[240:241], 0, s[74:75]
	s_mov_b32 m0, s8
	ds_read_b128 v[184:187], v194 offset:49152
	ds_read_b128 v[188:191], v194 offset:50176
	ds_read_b128 v[196:199], v194 offset:51200
	ds_read_b128 v[200:203], v194 offset:52224
	ds_read_b128 v[224:227], v194 offset:53248
	ds_read_b128 v[228:231], v194 offset:54272
	ds_read_b128 v[232:235], v194 offset:55296
	ds_read_b128 v[236:239], v194 offset:56320
	global_load_lds_dwordx4 v[240:241], off
	v_lshl_add_u64 v[240:241], v[242:243], 0, s[74:75]
	s_add_i32 m0, s8, 0x2000
	s_add_i32 s8, s64, s48
	global_load_lds_dwordx4 v[240:241], off
	v_lshl_add_u64 v[240:241], v[244:245], 0, s[74:75]
	s_mov_b32 m0, s8
	s_nop 0
	global_load_lds_dwordx4 v[240:241], off
	v_lshl_add_u64 v[240:241], v[246:247], 0, s[74:75]
	s_add_i32 m0, s8, 0x2000
	s_nop 0
	global_load_lds_dwordx4 v[240:241], off
	v_lshl_add_u64 v[240:241], v[248:249], 0, s[74:75]
	s_mov_b32 m0, s36
	s_nop 0
	global_load_lds_dwordx4 v[240:241], off
	v_lshl_add_u64 v[240:241], v[250:251], 0, s[74:75]
	s_mov_b32 m0, s37
	s_nop 0
	global_load_lds_dwordx4 v[240:241], off
	s_waitcnt vmcnt(8)
	s_waitcnt lgkmcnt(0)
	s_barrier
	s_setprio 1
	s_waitcnt lgkmcnt(0)
	v_mfma_f32_16x16x32_bf16 v[62:65], v[130:133], v[184:187], v[62:65]
	v_mfma_f32_16x16x32_bf16 v[58:61], v[138:141], v[184:187], v[58:61]
	v_mfma_f32_16x16x32_bf16 v[46:49], v[130:133], v[196:199], v[46:49]
	v_mfma_f32_16x16x32_bf16 v[42:45], v[138:141], v[196:199], v[42:45]
	v_mfma_f32_16x16x32_bf16 v[30:33], v[130:133], v[224:227], v[30:33]
	v_mfma_f32_16x16x32_bf16 v[26:29], v[138:141], v[224:227], v[26:29]
	v_mfma_f32_16x16x32_bf16 v[14:17], v[130:133], v[232:235], v[14:17]
	v_mfma_f32_16x16x32_bf16 v[10:13], v[138:141], v[232:235], v[10:13]
	s_setprio 0
	s_setprio 1
	v_mfma_f32_16x16x32_bf16 v[62:65], v[134:137], v[188:191], v[62:65]
	v_mfma_f32_16x16x32_bf16 v[58:61], v[142:145], v[188:191], v[58:61]
	v_mfma_f32_16x16x32_bf16 v[46:49], v[134:137], v[200:203], v[46:49]
	v_mfma_f32_16x16x32_bf16 v[42:45], v[142:145], v[200:203], v[42:45]
	v_mfma_f32_16x16x32_bf16 v[30:33], v[134:137], v[228:231], v[30:33]
	v_mfma_f32_16x16x32_bf16 v[26:29], v[142:145], v[228:231], v[26:29]
	v_mfma_f32_16x16x32_bf16 v[14:17], v[134:137], v[236:239], v[14:17]
	v_mfma_f32_16x16x32_bf16 v[10:13], v[142:145], v[236:239], v[10:13]
	s_setprio 0
	s_setprio 1
	v_mfma_f32_16x16x32_bf16 v[54:57], v[146:149], v[184:187], v[54:57]
	v_mfma_f32_16x16x32_bf16 v[50:53], v[176:179], v[184:187], v[50:53]
	v_mfma_f32_16x16x32_bf16 v[38:41], v[146:149], v[196:199], v[38:41]
	v_mfma_f32_16x16x32_bf16 v[34:37], v[176:179], v[196:199], v[34:37]
	v_mfma_f32_16x16x32_bf16 v[22:25], v[146:149], v[224:227], v[22:25]
	v_mfma_f32_16x16x32_bf16 v[18:21], v[176:179], v[224:227], v[18:21]
	v_mfma_f32_16x16x32_bf16 v[6:9], v[146:149], v[232:235], v[6:9]
	v_mfma_f32_16x16x32_bf16 v[2:5], v[176:179], v[232:235], v[2:5]
	s_setprio 0
	s_setprio 1
	v_mfma_f32_16x16x32_bf16 v[54:57], v[150:153], v[188:191], v[54:57]
	v_mfma_f32_16x16x32_bf16 v[50:53], v[180:183], v[188:191], v[50:53]
	v_mfma_f32_16x16x32_bf16 v[38:41], v[150:153], v[200:203], v[38:41]
	v_mfma_f32_16x16x32_bf16 v[34:37], v[180:183], v[200:203], v[34:37]
	v_mfma_f32_16x16x32_bf16 v[22:25], v[150:153], v[228:231], v[22:25]
	v_mfma_f32_16x16x32_bf16 v[18:21], v[180:183], v[228:231], v[18:21]
	v_mfma_f32_16x16x32_bf16 v[6:9], v[150:153], v[236:239], v[6:9]
	v_mfma_f32_16x16x32_bf16 v[2:5], v[180:183], v[236:239], v[2:5]
	s_setprio 0
	s_barrier
	s_add_u32 s62, s62, 0x100
	s_addc_u32 s63, s63, 0
	s_add_u32 s4, s4, 0x100
	s_addc_u32 s5, s5, 0
	s_cmp_ge_i32 s28, s52
	s_mov_b32 s8, s28
	s_cbranch_scc0 .LBB0_690

; #define PG8_STAGE(bufoff, gbase, voff) do { _Pragma("unroll") for (int _i = 0; _i < 2; ++_i) \
;         __builtin_amdgcn_global_load_lds((const unsigned*)((const char*)(gbase) + (voff)[_i]), (LAS unsigned*)(lds + (bufoff) + ldsw + _i * 8192), 16, 0, 0); } while (0)
; #define PG8_LDA(dst, b, h) do { _Pragma("unroll") for (int m = 0; m < 4; ++m) _Pragma("unroll") for (int k = 0; k < 2; ++k) dst[m][k] = *(const LAS bf16x8*)(lds + PG8_SA(b, h) + aoff + m * 2048 + k * 1024); } while (0)
; #define PG8_LDB(dst, b, h) do { _Pragma("unroll") for (int n = 0; n < 2; ++n) _Pragma("unroll") for (int k = 0; k < 2; ++k) dst[n][k] = *(const LAS bf16x8*)(lds + PG8_SB(b, h) + boff + n * 2048 + k * 1024); } while (0)
; #define PG8_MMA(ai, bj, At, Bt) do { __builtin_amdgcn_s_setprio(1); _Pragma("unroll") for (int m = 0; m < 4; ++m) _Pragma("unroll") for (int n = 0; n < 2; ++n) _Pragma("unroll") for (int k = 0; k < 2; ++k) \
;         acc[ai][bj][m][n] = __builtin_amdgcn_mfma_f32_16x16x32_bf16(Bt[n][k], At[m][k], acc[ai][bj][m][n], 0, 0, 0); __builtin_amdgcn_s_setprio(0); } while (0)
; #define PG8_WAIT_V(n) asm volatile("s_waitcnt vmcnt(" #n ")" ::: "memory")
; #define PG8_WAIT_L(n) asm volatile("s_waitcnt lgkmcnt(" #n ")" ::: "memory")
; #define PG8_BAR __builtin_amdgcn_s_barrier()
; #define PG8_SCHED __builtin_amdgcn_sched_barrier(0)
; template <class Epi>
; __device__ __forceinline__ void gemm_phase(LAS unsigned char* lds, const Gemm g, const StaticOrder& S, const Epi& E) {
;     ...
;             const bool last = (t == nt - 2);
;             const char* a1 = cA + (size_t)(t + 1) * kstep;
;             const char* a2 = last ? nA : cA + (size_t)(t + 2) * kstep; const char* b2 = last ? nB : cB + (size_t)(t + 2) * kstep;
;             const char* a3 = a2 + kstep; const char* b3 = b2 + kstep;
;             PG8_LDB(B0, 0, 0); PG8_LDB(B1, 0, 1); PG8_SCHED; PG8_LDA(At, 0, 0); PG8_STAGE(PG8_SA(1, 1), a1 + hstepA, voffA);
;             PG8_WAIT_V(8); PG8_WAIT_L(0); PG8_BAR; PG8_MMA(0, 0, At, B0); PG8_MMA(0, 1, At, B1); PG8_BAR; PG8_SCHED;
;             PG8_LDA(At, 0, 1); PG8_STAGE(PG8_SB(0, 0), b2, voffB); PG8_STAGE(PG8_SB(0, 1), b2 + hstepB, voffB); PG8_STAGE(PG8_SA(0, 0), a2, voffA);
;             PG8_WAIT_V(8); PG8_WAIT_L(0); PG8_BAR; PG8_MMA(1, 0, At, B0); PG8_MMA(1, 1, At, B1); PG8_BAR; PG8_SCHED;
.LBB0_727:
	s_add_i32 s55, s28, 2
	s_add_u32 s29, s4, 0xfff80080
	s_addc_u32 s34, s5, -1
	s_add_i32 s56, 0, 0x10000
	s_cmp_eq_u32 s50, s28
	s_cselect_b32 s35, s19, s34
	s_cselect_b32 s34, s21, s29
	v_add_u32_e32 v152, s56, v173
	s_cselect_b32 s29, s36, s54
	s_cselect_b32 s28, s37, s53
	s_add_i32 s58, 0, 0x14000
	ds_read_b128 v[130:133], v152
	ds_read_b128 v[134:137], v152 offset:1024
	ds_read_b128 v[148:151], v152 offset:2048
	ds_read_b128 v[166:169], v152 offset:3072
	v_add_u32_e32 v152, s58, v173
	ds_read_b128 v[176:179], v152
	ds_read_b128 v[180:183], v152 offset:1024
	ds_read_b128 v[184:187], v152 offset:2048
	ds_read_b128 v[188:191], v152 offset:3072
	v_lshl_add_u64 v[152:153], s[4:5], 0, v[146:147]
	s_add_i32 m0, s41, 0xc000
	ds_read_b128 v[192:195], v175
	ds_read_b128 v[196:199], v175 offset:1024
	ds_read_b128 v[200:203], v175 offset:2048
	ds_read_b128 v[224:227], v175 offset:3072
	ds_read_b128 v[228:231], v175 offset:4096
	ds_read_b128 v[232:235], v175 offset:5120
	ds_read_b128 v[236:239], v175 offset:6144
	ds_read_b128 v[240:243], v175 offset:7168
	global_load_lds_dwordx4 v[152:153], off
	v_lshl_add_u64 v[152:153], s[4:5], 0, v[144:145]
	s_add_i32 m0, s41, 0xe000
	s_nop 0
	global_load_lds_dwordx4 v[152:153], off
	s_waitcnt vmcnt(8)
	s_waitcnt lgkmcnt(0)
	s_barrier
	s_setprio 1
	s_waitcnt lgkmcnt(0)
	v_mfma_f32_16x16x32_bf16 v[122:125], v[130:133], v[192:195], v[122:125]
	v_mfma_f32_16x16x32_bf16 v[114:117], v[148:151], v[192:195], v[114:117]
	v_mfma_f32_16x16x32_bf16 v[106:109], v[130:133], v[200:203], v[106:109]
	v_mfma_f32_16x16x32_bf16 v[98:101], v[148:151], v[200:203], v[98:101]
	v_mfma_f32_16x16x32_bf16 v[90:93], v[130:133], v[228:231], v[90:93]
	v_mfma_f32_16x16x32_bf16 v[82:85], v[148:151], v[228:231], v[82:85]
	v_mfma_f32_16x16x32_bf16 v[74:77], v[130:133], v[236:239], v[74:77]
	v_mfma_f32_16x16x32_bf16 v[66:69], v[148:151], v[236:239], v[66:69]
	s_setprio 0
	s_setprio 1
	v_mfma_f32_16x16x32_bf16 v[122:125], v[134:137], v[196:199], v[122:125]
	v_mfma_f32_16x16x32_bf16 v[114:117], v[166:169], v[196:199], v[114:117]
	v_mfma_f32_16x16x32_bf16 v[106:109], v[134:137], v[224:227], v[106:109]
	v_mfma_f32_16x16x32_bf16 v[98:101], v[166:169], v[224:227], v[98:101]
	v_mfma_f32_16x16x32_bf16 v[90:93], v[134:137], v[232:235], v[90:93]
	v_mfma_f32_16x16x32_bf16 v[82:85], v[166:169], v[232:235], v[82:85]
	v_mfma_f32_16x16x32_bf16 v[74:77], v[134:137], v[240:243], v[74:77]
	v_mfma_f32_16x16x32_bf16 v[66:69], v[166:169], v[240:243], v[66:69]
	s_setprio 0
	s_setprio 1
	v_mfma_f32_16x16x32_bf16 v[126:129], v[176:179], v[192:195], v[126:129]
	v_mfma_f32_16x16x32_bf16 v[118:121], v[184:187], v[192:195], v[118:121]
	v_mfma_f32_16x16x32_bf16 v[110:113], v[176:179], v[200:203], v[110:113]
	v_mfma_f32_16x16x32_bf16 v[102:105], v[184:187], v[200:203], v[102:105]
	v_mfma_f32_16x16x32_bf16 v[94:97], v[176:179], v[228:231], v[94:97]
	v_mfma_f32_16x16x32_bf16 v[86:89], v[184:187], v[228:231], v[86:89]
	v_mfma_f32_16x16x32_bf16 v[78:81], v[176:179], v[236:239], v[78:81]
	v_mfma_f32_16x16x32_bf16 v[70:73], v[184:187], v[236:239], v[70:73]
	s_setprio 0
	s_setprio 1
	v_mfma_f32_16x16x32_bf16 v[126:129], v[180:183], v[196:199], v[126:129]
	v_mfma_f32_16x16x32_bf16 v[118:121], v[188:191], v[196:199], v[118:121]
	v_mfma_f32_16x16x32_bf16 v[110:113], v[180:183], v[224:227], v[110:113]
	v_mfma_f32_16x16x32_bf16 v[102:105], v[188:191], v[224:227], v[102:105]
	v_mfma_f32_16x16x32_bf16 v[94:97], v[180:183], v[232:235], v[94:97]
	v_mfma_f32_16x16x32_bf16 v[86:89], v[188:191], v[232:235], v[86:89]
	v_mfma_f32_16x16x32_bf16 v[78:81], v[180:183], v[240:243], v[78:81]
	v_mfma_f32_16x16x32_bf16 v[70:73], v[188:191], v[240:243], v[70:73]
	s_setprio 0
	s_barrier
	s_add_i32 s56, s56, s39
	v_lshl_add_u64 v[152:153], s[28:29], 0, v[0:1]
	s_mov_b32 m0, s56
	ds_read_b128 v[192:195], v175 offset:16384
	ds_read_b128 v[196:199], v175 offset:17408
	ds_read_b128 v[200:203], v175 offset:18432
	ds_read_b128 v[224:227], v175 offset:19456
	ds_read_b128 v[228:231], v175 offset:20480
	ds_read_b128 v[232:235], v175 offset:21504
	ds_read_b128 v[236:239], v175 offset:22528
	ds_read_b128 v[240:243], v175 offset:23552
	global_load_lds_dwordx4 v[152:153], off
	s_add_i32 m0, s56, 0x2000
	s_add_u32 s56, s28, 0x80000
	v_lshl_add_u64 v[244:245], s[28:29], 0, v[138:139]
	s_addc_u32 s57, s29, 0
	s_add_i32 s58, s58, s39
	global_load_lds_dwordx4 v[244:245], off
	v_lshl_add_u64 v[246:247], s[56:57], 0, v[0:1]
	s_mov_b32 m0, s58
	v_lshl_add_u64 v[248:249], s[34:35], 0, v[140:141]
	global_load_lds_dwordx4 v[246:247], off
	v_lshl_add_u64 v[246:247], s[56:57], 0, v[138:139]
	s_add_i32 m0, s58, 0x2000
	s_nop 0
	global_load_lds_dwordx4 v[246:247], off
	v_lshl_add_u64 v[246:247], s[34:35], 0, v[142:143]
	s_mov_b32 m0, s41
	s_nop 0
	global_load_lds_dwordx4 v[246:247], off
	s_mov_b32 m0, s42
	s_nop 0
	global_load_lds_dwordx4 v[248:249], off
	s_waitcnt vmcnt(8)
	s_waitcnt lgkmcnt(0)
	s_barrier
; #define PG8_STAGE(bufoff, gbase, voff) do { _Pragma("unroll") for (int _i = 0; _i < 2; ++_i) \
;         __builtin_amdgcn_global_load_lds((const unsigned*)((const char*)(gbase) + (voff)[_i]), (LAS unsigned*)(lds + (bufoff) + ldsw + _i * 8192), 16, 0, 0); } while (0)
; #define PG8_LDA(dst, b, h) do { _Pragma("unroll") for (int m = 0; m < 4; ++m) _Pragma("unroll") for (int k = 0; k < 2; ++k) dst[m][k] = *(const LAS bf16x8*)(lds + PG8_SA(b, h) + aoff + m * 2048 + k * 1024); } while (0)
; #define PG8_LDB(dst, b, h) do { _Pragma("unroll") for (int n = 0; n < 2; ++n) _Pragma("unroll") for (int k = 0; k < 2; ++k) dst[n][k] = *(const LAS bf16x8*)(lds + PG8_SB(b, h) + boff + n * 2048 + k * 1024); } while (0)
; #define PG8_MMA(ai, bj, At, Bt) do { __builtin_amdgcn_s_setprio(1); _Pragma("unroll") for (int m = 0; m < 4; ++m) _Pragma("unroll") for (int n = 0; n < 2; ++n) _Pragma("unroll") for (int k = 0; k < 2; ++k) \
;         acc[ai][bj][m][n] = __builtin_amdgcn_mfma_f32_16x16x32_bf16(Bt[n][k], At[m][k], acc[ai][bj][m][n], 0, 0, 0); __builtin_amdgcn_s_setprio(0); } while (0)
; #define PG8_WAIT_V(n) asm volatile("s_waitcnt vmcnt(" #n ")" ::: "memory")
; #define PG8_WAIT_L(n) asm volatile("s_waitcnt lgkmcnt(" #n ")" ::: "memory")
; #define PG8_BAR __builtin_amdgcn_s_barrier()
; #define PG8_SCHED __builtin_amdgcn_sched_barrier(0)
; template <class Epi>
; __device__ __forceinline__ void gemm_phase(LAS unsigned char* lds, const Gemm g, const StaticOrder& S, const Epi& E) {
;     ...
;             PG8_WAIT_V(8); PG8_WAIT_L(0); PG8_BAR; PG8_MMA(1, 0, At, B0); PG8_MMA(1, 1, At, B1); PG8_BAR; PG8_SCHED;
;             PG8_LDB(B0, 1, 0); PG8_LDB(B1, 1, 1); PG8_SCHED; PG8_LDA(At, 1, 0); PG8_STAGE(PG8_SA(0, 1), a2 + hstepA, voffA);
;             PG8_WAIT_V(8); PG8_WAIT_L(0); PG8_BAR; PG8_MMA(0, 0, At, B0); PG8_MMA(0, 1, At, B1); PG8_BAR; PG8_SCHED;
	s_setprio 1
	s_waitcnt lgkmcnt(0)
	v_mfma_f32_16x16x32_bf16 v[58:61], v[130:133], v[192:195], v[58:61]
	v_mfma_f32_16x16x32_bf16 v[50:53], v[148:151], v[192:195], v[50:53]
	v_mfma_f32_16x16x32_bf16 v[42:45], v[130:133], v[200:203], v[42:45]
	v_mfma_f32_16x16x32_bf16 v[34:37], v[148:151], v[200:203], v[34:37]
	v_mfma_f32_16x16x32_bf16 v[26:29], v[130:133], v[228:231], v[26:29]
	v_mfma_f32_16x16x32_bf16 v[18:21], v[148:151], v[228:231], v[18:21]
	v_mfma_f32_16x16x32_bf16 v[10:13], v[130:133], v[236:239], v[10:13]
	v_mfma_f32_16x16x32_bf16 v[6:9], v[148:151], v[236:239], v[6:9]
	s_setprio 0
	s_setprio 1
	v_mfma_f32_16x16x32_bf16 v[58:61], v[134:137], v[196:199], v[58:61]
	v_mfma_f32_16x16x32_bf16 v[50:53], v[166:169], v[196:199], v[50:53]
	v_mfma_f32_16x16x32_bf16 v[42:45], v[134:137], v[224:227], v[42:45]
	v_mfma_f32_16x16x32_bf16 v[34:37], v[166:169], v[224:227], v[34:37]
	v_mfma_f32_16x16x32_bf16 v[26:29], v[134:137], v[232:235], v[26:29]
	v_mfma_f32_16x16x32_bf16 v[18:21], v[166:169], v[232:235], v[18:21]
	v_mfma_f32_16x16x32_bf16 v[10:13], v[134:137], v[240:243], v[10:13]
	v_mfma_f32_16x16x32_bf16 v[6:9], v[166:169], v[240:243], v[6:9]
	s_setprio 0
	s_setprio 1
	v_mfma_f32_16x16x32_bf16 v[62:65], v[176:179], v[192:195], v[62:65]
	v_mfma_f32_16x16x32_bf16 v[54:57], v[184:187], v[192:195], v[54:57]
	v_mfma_f32_16x16x32_bf16 v[46:49], v[176:179], v[200:203], v[46:49]
	v_mfma_f32_16x16x32_bf16 v[38:41], v[184:187], v[200:203], v[38:41]
	v_mfma_f32_16x16x32_bf16 v[30:33], v[176:179], v[228:231], v[30:33]
	v_mfma_f32_16x16x32_bf16 v[22:25], v[184:187], v[228:231], v[22:25]
	v_mfma_f32_16x16x32_bf16 v[14:17], v[176:179], v[236:239], v[14:17]
	v_mfma_f32_16x16x32_bf16 v[2:5], v[184:187], v[236:239], v[2:5]
	s_setprio 0
	s_setprio 1
	v_mfma_f32_16x16x32_bf16 v[62:65], v[180:183], v[196:199], v[62:65]
	v_mfma_f32_16x16x32_bf16 v[54:57], v[188:191], v[196:199], v[54:57]
	v_mfma_f32_16x16x32_bf16 v[46:49], v[180:183], v[224:227], v[46:49]
	v_mfma_f32_16x16x32_bf16 v[38:41], v[188:191], v[224:227], v[38:41]
	v_mfma_f32_16x16x32_bf16 v[30:33], v[180:183], v[232:235], v[30:33]
	v_mfma_f32_16x16x32_bf16 v[22:25], v[188:191], v[232:235], v[22:25]
	v_mfma_f32_16x16x32_bf16 v[14:17], v[180:183], v[240:243], v[14:17]
	v_mfma_f32_16x16x32_bf16 v[2:5], v[188:191], v[240:243], v[2:5]
	s_setprio 0
	s_barrier
	s_add_i32 s56, 0, 0x18000
	s_add_i32 s57, 0, 0x1c000
	v_add_u32_e32 v166, s56, v173
	v_add_u32_e32 v170, s57, v173
	ds_read_b128 v[130:133], v166
	ds_read_b128 v[134:137], v166 offset:1024
	ds_read_b128 v[148:151], v166 offset:2048
	ds_read_b128 v[166:169], v166 offset:3072
	ds_read_b128 v[176:179], v170
	ds_read_b128 v[180:183], v170 offset:1024
	ds_read_b128 v[184:187], v170 offset:2048
	ds_read_b128 v[188:191], v170 offset:3072
	s_add_u32 s34, s34, 0x80000
	s_addc_u32 s35, s35, 0
	s_mov_b32 m0, s43
	v_lshl_add_u64 v[250:251], s[34:35], 0, v[142:143]
	ds_read_b128 v[192:195], v175 offset:32768
	ds_read_b128 v[196:199], v175 offset:33792
	ds_read_b128 v[200:203], v175 offset:34816
	ds_read_b128 v[224:227], v175 offset:35840
	ds_read_b128 v[228:231], v175 offset:36864
	ds_read_b128 v[232:235], v175 offset:37888
	ds_read_b128 v[236:239], v175 offset:38912
	ds_read_b128 v[240:243], v175 offset:39936
	global_load_lds_dwordx4 v[250:251], off
	v_lshl_add_u64 v[250:251], s[34:35], 0, v[140:141]
	s_mov_b32 m0, s44
	s_nop 0
	global_load_lds_dwordx4 v[250:251], off
	s_waitcnt vmcnt(8)
	s_waitcnt lgkmcnt(0)
	s_barrier
	s_setprio 1
	s_waitcnt lgkmcnt(0)
	v_mfma_f32_16x16x32_bf16 v[122:125], v[130:133], v[192:195], v[122:125]
	v_mfma_f32_16x16x32_bf16 v[114:117], v[148:151], v[192:195], v[114:117]
	v_mfma_f32_16x16x32_bf16 v[106:109], v[130:133], v[200:203], v[106:109]
	v_mfma_f32_16x16x32_bf16 v[98:101], v[148:151], v[200:203], v[98:101]
	v_mfma_f32_16x16x32_bf16 v[90:93], v[130:133], v[228:231], v[90:93]
	v_mfma_f32_16x16x32_bf16 v[82:85], v[148:151], v[228:231], v[82:85]
	v_mfma_f32_16x16x32_bf16 v[74:77], v[130:133], v[236:239], v[74:77]
	v_mfma_f32_16x16x32_bf16 v[66:69], v[148:151], v[236:239], v[66:69]
	s_setprio 0
	s_setprio 1
	v_mfma_f32_16x16x32_bf16 v[122:125], v[134:137], v[196:199], v[122:125]
	v_mfma_f32_16x16x32_bf16 v[114:117], v[166:169], v[196:199], v[114:117]
	v_mfma_f32_16x16x32_bf16 v[106:109], v[134:137], v[224:227], v[106:109]
	v_mfma_f32_16x16x32_bf16 v[98:101], v[166:169], v[224:227], v[98:101]
	v_mfma_f32_16x16x32_bf16 v[90:93], v[134:137], v[232:235], v[90:93]
	v_mfma_f32_16x16x32_bf16 v[82:85], v[166:169], v[232:235], v[82:85]
	v_mfma_f32_16x16x32_bf16 v[74:77], v[134:137], v[240:243], v[74:77]
	v_mfma_f32_16x16x32_bf16 v[66:69], v[166:169], v[240:243], v[66:69]
	s_setprio 0
	s_setprio 1
	v_mfma_f32_16x16x32_bf16 v[126:129], v[176:179], v[192:195], v[126:129]
	v_mfma_f32_16x16x32_bf16 v[118:121], v[184:187], v[192:195], v[118:121]
	v_mfma_f32_16x16x32_bf16 v[110:113], v[176:179], v[200:203], v[110:113]
	v_mfma_f32_16x16x32_bf16 v[102:105], v[184:187], v[200:203], v[102:105]
	v_mfma_f32_16x16x32_bf16 v[94:97], v[176:179], v[228:231], v[94:97]
	v_mfma_f32_16x16x32_bf16 v[86:89], v[184:187], v[228:231], v[86:89]
	v_mfma_f32_16x16x32_bf16 v[78:81], v[176:179], v[236:239], v[78:81]
	v_mfma_f32_16x16x32_bf16 v[70:73], v[184:187], v[236:239], v[70:73]
	s_setprio 0
	s_setprio 1
	v_mfma_f32_16x16x32_bf16 v[126:129], v[180:183], v[196:199], v[126:129]
	v_mfma_f32_16x16x32_bf16 v[118:121], v[188:191], v[196:199], v[118:121]
	v_mfma_f32_16x16x32_bf16 v[110:113], v[180:183], v[224:227], v[110:113]
	v_mfma_f32_16x16x32_bf16 v[102:105], v[188:191], v[224:227], v[102:105]
	v_mfma_f32_16x16x32_bf16 v[94:97], v[180:183], v[232:235], v[94:97]
	v_mfma_f32_16x16x32_bf16 v[86:89], v[188:191], v[232:235], v[86:89]
	v_mfma_f32_16x16x32_bf16 v[78:81], v[180:183], v[240:243], v[78:81]
	v_mfma_f32_16x16x32_bf16 v[70:73], v[188:191], v[240:243], v[70:73]
	s_setprio 0
	s_barrier
; #define PG8_STAGE(bufoff, gbase, voff) do { _Pragma("unroll") for (int _i = 0; _i < 2; ++_i) \
;         __builtin_amdgcn_global_load_lds((const unsigned*)((const char*)(gbase) + (voff)[_i]), (LAS unsigned*)(lds + (bufoff) + ldsw + _i * 8192), 16, 0, 0); } while (0)
; #define PG8_LDA(dst, b, h) do { _Pragma("unroll") for (int m = 0; m < 4; ++m) _Pragma("unroll") for (int k = 0; k < 2; ++k) dst[m][k] = *(const LAS bf16x8*)(lds + PG8_SA(b, h) + aoff + m * 2048 + k * 1024); } while (0)
; #define PG8_MMA(ai, bj, At, Bt) do { __builtin_amdgcn_s_setprio(1); _Pragma("unroll") for (int m = 0; m < 4; ++m) _Pragma("unroll") for (int n = 0; n < 2; ++n) _Pragma("unroll") for (int k = 0; k < 2; ++k) \
;         acc[ai][bj][m][n] = __builtin_amdgcn_mfma_f32_16x16x32_bf16(Bt[n][k], At[m][k], acc[ai][bj][m][n], 0, 0, 0); __builtin_amdgcn_s_setprio(0); } while (0)
; #define PG8_WAIT_V(n) asm volatile("s_waitcnt vmcnt(" #n ")" ::: "memory")
; #define PG8_WAIT_L(n) asm volatile("s_waitcnt lgkmcnt(" #n ")" ::: "memory")
; #define PG8_BAR __builtin_amdgcn_s_barrier()
; #define PG8_SCHED __builtin_amdgcn_sched_barrier(0)
; template <class Epi>
; __device__ __forceinline__ void gemm_phase(LAS unsigned char* lds, const Gemm g, const StaticOrder& S, const Epi& E) {
;     ...
;             PG8_LDA(At, 1, 1); PG8_STAGE(PG8_SB(1, 0), b3, voffB); PG8_STAGE(PG8_SB(1, 1), b3 + hstepB, voffB); PG8_STAGE(PG8_SA(1, 0), a3, voffA);
;             PG8_WAIT_V(8); PG8_WAIT_L(0); PG8_BAR; PG8_MMA(1, 0, At, B0); PG8_MMA(1, 1, At, B1); PG8_BAR; PG8_SCHED;
;         }
	s_add_i32 s34, s56, s39
	v_lshl_add_u64 v[152:153], v[152:153], 0, s[74:75]
	s_mov_b32 m0, s34
	ds_read_b128 v[192:195], v175 offset:49152
	ds_read_b128 v[196:199], v175 offset:50176
	ds_read_b128 v[200:203], v175 offset:51200
	ds_read_b128 v[224:227], v175 offset:52224
	ds_read_b128 v[228:231], v175 offset:53248
	ds_read_b128 v[232:235], v175 offset:54272
	ds_read_b128 v[236:239], v175 offset:55296
	ds_read_b128 v[240:243], v175 offset:56320
	global_load_lds_dwordx4 v[152:153], off
	s_add_i32 m0, s34, 0x2000
	s_add_u32 s28, s28, 0x80080
	v_lshl_add_u64 v[152:153], v[244:245], 0, s[74:75]
	s_addc_u32 s29, s29, 0
	s_add_i32 s34, s57, s39
	global_load_lds_dwordx4 v[152:153], off
	v_lshl_add_u64 v[152:153], s[28:29], 0, v[0:1]
	s_mov_b32 m0, s34
	s_nop 0
	global_load_lds_dwordx4 v[152:153], off
	v_lshl_add_u64 v[152:153], s[28:29], 0, v[138:139]
	s_add_i32 m0, s34, 0x2000
	s_nop 0
	global_load_lds_dwordx4 v[152:153], off
	v_lshl_add_u64 v[152:153], v[246:247], 0, s[74:75]
	s_mov_b32 m0, s48
	s_nop 0
	global_load_lds_dwordx4 v[152:153], off
	v_lshl_add_u64 v[152:153], v[248:249], 0, s[74:75]
	s_mov_b32 m0, s49
	s_nop 0
	global_load_lds_dwordx4 v[152:153], off
	s_waitcnt vmcnt(8)
	s_waitcnt lgkmcnt(0)
	s_barrier
	s_setprio 1
	s_waitcnt lgkmcnt(0)
	v_mfma_f32_16x16x32_bf16 v[58:61], v[130:133], v[192:195], v[58:61]
	v_mfma_f32_16x16x32_bf16 v[50:53], v[148:151], v[192:195], v[50:53]
	v_mfma_f32_16x16x32_bf16 v[42:45], v[130:133], v[200:203], v[42:45]
	v_mfma_f32_16x16x32_bf16 v[34:37], v[148:151], v[200:203], v[34:37]
	v_mfma_f32_16x16x32_bf16 v[26:29], v[130:133], v[228:231], v[26:29]
	v_mfma_f32_16x16x32_bf16 v[18:21], v[148:151], v[228:231], v[18:21]
	v_mfma_f32_16x16x32_bf16 v[10:13], v[130:133], v[236:239], v[10:13]
	v_mfma_f32_16x16x32_bf16 v[6:9], v[148:151], v[236:239], v[6:9]
	s_setprio 0
	s_setprio 1
	v_mfma_f32_16x16x32_bf16 v[58:61], v[134:137], v[196:199], v[58:61]
	v_mfma_f32_16x16x32_bf16 v[50:53], v[166:169], v[196:199], v[50:53]
	v_mfma_f32_16x16x32_bf16 v[42:45], v[134:137], v[224:227], v[42:45]
	v_mfma_f32_16x16x32_bf16 v[34:37], v[166:169], v[224:227], v[34:37]
	v_mfma_f32_16x16x32_bf16 v[26:29], v[134:137], v[232:235], v[26:29]
	v_mfma_f32_16x16x32_bf16 v[18:21], v[166:169], v[232:235], v[18:21]
	v_mfma_f32_16x16x32_bf16 v[10:13], v[134:137], v[240:243], v[10:13]
	v_mfma_f32_16x16x32_bf16 v[6:9], v[166:169], v[240:243], v[6:9]
	s_setprio 0
	s_setprio 1
	v_mfma_f32_16x16x32_bf16 v[62:65], v[176:179], v[192:195], v[62:65]
	v_mfma_f32_16x16x32_bf16 v[54:57], v[184:187], v[192:195], v[54:57]
	v_mfma_f32_16x16x32_bf16 v[46:49], v[176:179], v[200:203], v[46:49]
	v_mfma_f32_16x16x32_bf16 v[38:41], v[184:187], v[200:203], v[38:41]
	v_mfma_f32_16x16x32_bf16 v[30:33], v[176:179], v[228:231], v[30:33]
	v_mfma_f32_16x16x32_bf16 v[22:25], v[184:187], v[228:231], v[22:25]
	v_mfma_f32_16x16x32_bf16 v[14:17], v[176:179], v[236:239], v[14:17]
	v_mfma_f32_16x16x32_bf16 v[2:5], v[184:187], v[236:239], v[2:5]
	s_setprio 0
	s_setprio 1
	v_mfma_f32_16x16x32_bf16 v[62:65], v[180:183], v[196:199], v[62:65]
	v_mfma_f32_16x16x32_bf16 v[54:57], v[188:191], v[196:199], v[54:57]
	v_mfma_f32_16x16x32_bf16 v[46:49], v[180:183], v[224:227], v[46:49]
	v_mfma_f32_16x16x32_bf16 v[38:41], v[188:191], v[224:227], v[38:41]
	v_mfma_f32_16x16x32_bf16 v[30:33], v[180:183], v[232:235], v[30:33]
	v_mfma_f32_16x16x32_bf16 v[22:25], v[188:191], v[232:235], v[22:25]
	v_mfma_f32_16x16x32_bf16 v[14:17], v[180:183], v[240:243], v[14:17]
	v_mfma_f32_16x16x32_bf16 v[2:5], v[188:191], v[240:243], v[2:5]
	s_setprio 0
	s_barrier
	s_add_u32 s53, s53, 0x100
	s_addc_u32 s54, s54, 0
	s_add_u32 s4, s4, 0x100
	s_addc_u32 s5, s5, 0
	s_cmp_ge_i32 s55, s45
	s_mov_b32 s28, s55
	s_cbranch_scc0 .LBB0_727
